# static s_setprio 1 for the younger half (waves 4-7) across each GEMM main loop, all per-block priority flips removed; on top of the load-batching edits
# speedup vs baseline: 1.0040x; 1.0040x over previous
.LBB0_66:
	s_setprio 0
	v_readlane_b32 s0, v240, 31
	v_readlane_b32 s1, v240, 32
	s_mov_b32 s60, 1
	s_mov_b64 s[6:7], -1
	s_mov_b64 s[62:63], 0
	s_and_b64 vcc, exec, s[0:1]
	s_mov_b64 s[8:9], s[44:45]
	s_cbranch_vccnz .LBB0_1067

.LBB0_206:
	s_or_b64 exec, exec, s[8:9]
	s_mov_b64 s[18:19], s[76:77]
	s_waitcnt lgkmcnt(0)
	s_barrier
	s_load_dwordx2 s[50:51], s[18:19], 0xa8
	s_mul_i32 s0, s60, 0x6800000
	v_writelane_b32 v240, s0, 37
	v_readlane_b32 s0, v241, 9
	v_readlane_b32 s1, v241, 10
	s_waitcnt lgkmcnt(0)
	s_add_u32 s76, s50, 0xd400000
	v_mov_b32_e32 v8, v172
	v_cndmask_b32_e64 v0, 0, 1, s[0:1]
	v_cmp_ne_u32_e64 s[4:5], 1, v0
	s_addc_u32 s77, s51, 0
	s_andn2_b64 vcc, exec, s[0:1]
	v_writelane_b32 v240, s4, 38
	v_readfirstlane_b32 s0, v8
	s_nop 0
	v_writelane_b32 v240, s5, 39
	s_cbranch_vccnz .LBB0_366
	v_lshlrev_b32_e32 v0, 4, v8
	v_add_u32_e32 v1, 0x2000, v0
	v_ashrrev_i32_e32 v2, 31, v1
	v_lshrrev_b32_e32 v2, 22, v2
	v_add_u32_e32 v2, v1, v2
	v_ashrrev_i32_e32 v9, 10, v2
	v_mul_i32_i24_e32 v2, 0x400, v9
	v_sub_u32_e32 v1, v1, v2
	v_lshrrev_b32_e32 v2, 4, v1
	v_bitop3_b32 v1, v2, v1, 32 bitop3:0x6c
	v_ashrrev_i32_e32 v2, 31, v1
	v_lshrrev_b32_e32 v2, 26, v2
	v_add_u32_e32 v2, v1, v2
	v_lshlrev_b32_e32 v3, 3, v9
	v_ashrrev_i32_e32 v10, 6, v2
	v_and_b32_e32 v3, -16, v3
	v_add_u32_e32 v3, v10, v3
	v_and_b32_e32 v4, 3, v10
	s_mov_b32 s5, 0xfffe0
	v_lshrrev_b32_e32 v5, 2, v3
	v_lshlrev_b32_e32 v6, 1, v3
	v_and_b32_e32 v2, 0xc0, v2
	v_and_or_b32 v4, v3, s5, v4
	v_and_b32_e32 v5, 4, v5
	v_and_b32_e32 v6, 24, v6
	v_sub_u32_e32 v1, v1, v2
	v_or3_b32 v4, v4, v5, v6
	v_lshlrev_b32_e32 v5, 5, v9
	v_ashrrev_i16_sdwa v1, v180, sext(v1) dst_sel:DWORD dst_unused:UNUSED_PAD src0_sel:DWORD src1_sel:BYTE_0
	v_and_b32_e32 v5, 32, v5
	v_bfe_i32 v11, v1, 0, 16
	v_add_lshl_u32 v1, v5, v11, 1
	v_lshl_add_u32 v136, v4, 12, v1
	v_lshl_add_u32 v138, v3, 12, v1
	v_bfe_i32 v1, v8, 27, 1
	v_lshrrev_b32_e32 v1, 22, v1
	v_add_u32_e32 v1, v0, v1
	v_and_b32_e32 v1, 0xfffffc00, v1
	v_sub_u32_e32 v0, v0, v1
	v_lshrrev_b32_e32 v1, 4, v0
	v_ashrrev_i32_e32 v2, 31, v8
	v_bitop3_b32 v0, v1, v0, 32 bitop3:0x6c
	v_lshrrev_b32_e32 v2, 26, v2
	v_ashrrev_i32_e32 v1, 31, v0
	v_add_u32_e32 v2, v8, v2
	v_lshrrev_b32_e32 v1, 26, v1
	v_ashrrev_i32_e32 v13, 6, v2
	s_mul_i32 s1, s60, 0x6800000
	v_add_u32_e32 v1, v0, v1
	v_lshlrev_b32_e32 v2, 3, v13
	s_add_u32 s1, s50, s1
	v_ashrrev_i32_e32 v12, 6, v1
	v_and_b32_e32 v2, -16, v2
	s_addc_u32 s4, s51, 0
	v_add_u32_e32 v2, v12, v2
	s_add_u32 s58, s1, 0x200000
	v_and_b32_e32 v3, 3, v12
	v_lshrrev_b32_e32 v4, 2, v2
	v_lshlrev_b32_e32 v5, 1, v2
	v_and_b32_e32 v1, 0xc0, v1
	s_addc_u32 s61, s4, 0
	s_ashr_i32 s4, s0, 6
	v_and_or_b32 v3, v2, s5, v3
	v_and_b32_e32 v4, 4, v4
	v_and_b32_e32 v5, 24, v5
	v_sub_u32_e32 v0, v0, v1
	s_ashr_i32 s1, s0, 8
	s_lshl_b32 s8, s4, 10
	v_or3_b32 v3, v3, v4, v5
	v_lshlrev_b32_e32 v4, 5, v13
	v_ashrrev_i16_sdwa v0, v180, sext(v0) dst_sel:DWORD dst_unused:UNUSED_PAD src0_sel:DWORD src1_sel:BYTE_0
	v_readlane_b32 s10, v240, 4
	v_and_b32_e32 v4, 32, v4
	v_bfe_i32 v14, v0, 0, 16
	v_readlane_b32 s11, v240, 5
	s_add_u32 s14, s58, s10
	v_add_lshl_u32 v0, v4, v14, 1
	s_addc_u32 s15, s61, s11
	s_add_i32 s9, s8, 0
	v_lshl_add_u32 v140, v3, 12, v0
	s_add_i32 m0, s9, 0x10000
	v_lshl_add_u32 v142, v2, 12, v0
	global_load_lds_dwordx4 v140, s[14:15]
	s_add_i32 m0, s9, 0x12000
	s_add_u32 s10, s14, 0x80000
	global_load_lds_dwordx4 v136, s[14:15]
	s_addc_u32 s11, s15, 0
	s_add_i32 m0, s9, 0x14000
	v_mov_b32_e32 v141, v145
	global_load_lds_dwordx4 v140, s[10:11]
	s_add_i32 m0, s9, 0x16000
	v_mov_b32_e32 v137, v145
	global_load_lds_dwordx4 v136, s[10:11]
	v_readlane_b32 s10, v240, 24
	v_readlane_b32 s11, v240, 25
	s_add_u32 s12, s76, s10
	s_addc_u32 s13, s77, s11
	s_add_i32 s35, s9, 0x2000
	s_mov_b32 m0, s9
	s_add_u32 s10, s12, 0x80000
	global_load_lds_dwordx4 v142, s[12:13]
	s_mov_b32 m0, s35
	s_addc_u32 s11, s13, 0
	s_add_i32 s5, s9, 0x4000
	global_load_lds_dwordx4 v138, s[12:13]
	s_mov_b32 m0, s5
	s_add_i32 s26, s9, 0x6000
	global_load_lds_dwordx4 v142, s[10:11]
	s_mov_b32 m0, s26
	v_mov_b32_e32 v143, v145
	global_load_lds_dwordx4 v138, s[10:11]
	v_mov_b32_e32 v139, v145
	s_cmp_eq_u32 s1, 1
	v_lshl_add_u64 v[6:7], s[14:15], 0, v[140:141]
	v_lshl_add_u64 v[4:5], s[14:15], 0, v[136:137]
	v_lshl_add_u64 v[0:1], s[12:13], 0, v[142:143]
	s_cselect_b64 s[20:21], -1, 0
	s_cmp_lg_u32 s1, 1
	v_lshl_add_u64 v[2:3], s[12:13], 0, v[138:139]
	s_cbranch_scc1 .LBB0_209
	s_barrier
	s_setprio 1

.LBB0_215:
	s_add_u32 s14, s12, 0xfff80080
	s_addc_u32 s15, s13, -1
	s_add_i32 s67, 0, 0x10000
	s_cmp_eq_u32 s53, 28
	s_cselect_b32 s17, s39, s15
	s_cselect_b32 s16, s47, s14
	v_add_u32_e32 v144, s67, v185
	s_cselect_b32 s15, s31, s52
	s_cselect_b32 s14, s48, s49
	s_add_i32 s82, 0, 0x14000
	ds_read_b128 v[88:91], v144
	ds_read_b128 v[92:95], v144 offset:1024
	ds_read_b128 v[158:161], v144 offset:2048
	ds_read_b128 v[162:165], v144 offset:3072
	v_add_u32_e32 v144, s82, v185
	ds_read_b128 v[166:169], v144
	ds_read_b128 v[188:191], v144 offset:1024
	ds_read_b128 v[192:195], v144 offset:2048
	ds_read_b128 v[196:199], v144 offset:3072
	v_lshl_add_u64 v[170:171], s[12:13], 0, v[154:155]
	s_add_i32 m0, s9, 0xc000
	ds_read_b128 v[200:203], v187
	ds_read_b128 v[204:207], v187 offset:1024
	ds_read_b128 v[208:211], v187 offset:2048
	ds_read_b128 v[212:215], v187 offset:3072
	ds_read_b128 v[216:219], v187 offset:4096
	ds_read_b128 v[220:223], v187 offset:5120
	ds_read_b128 v[224:227], v187 offset:6144
	ds_read_b128 v[228:231], v187 offset:7168
	global_load_lds_dwordx4 v[170:171], off
	v_lshl_add_u64 v[170:171], s[12:13], 0, v[156:157]
	s_add_i32 m0, s9, 0xe000
	s_nop 0
	global_load_lds_dwordx4 v[170:171], off
	s_waitcnt vmcnt(8)
	s_waitcnt lgkmcnt(0)
	s_barrier
	s_waitcnt lgkmcnt(0)
	v_mfma_f32_16x16x32_bf16 v[132:135], v[88:91], v[200:203], v[132:135]
	v_mfma_f32_16x16x32_bf16 v[128:131], v[158:161], v[200:203], v[128:131]
	v_mfma_f32_16x16x32_bf16 v[124:127], v[88:91], v[208:211], v[124:127]
	v_mfma_f32_16x16x32_bf16 v[120:123], v[158:161], v[208:211], v[120:123]
	v_mfma_f32_16x16x32_bf16 v[116:119], v[88:91], v[216:219], v[116:119]
	v_mfma_f32_16x16x32_bf16 v[112:115], v[158:161], v[216:219], v[112:115]
	v_mfma_f32_16x16x32_bf16 v[108:111], v[88:91], v[224:227], v[108:111]
	v_mfma_f32_16x16x32_bf16 v[104:107], v[158:161], v[224:227], v[104:107]
	v_mfma_f32_16x16x32_bf16 v[132:135], v[92:95], v[204:207], v[132:135]
	v_mfma_f32_16x16x32_bf16 v[128:131], v[162:165], v[204:207], v[128:131]
	v_mfma_f32_16x16x32_bf16 v[124:127], v[92:95], v[212:215], v[124:127]
	v_mfma_f32_16x16x32_bf16 v[120:123], v[162:165], v[212:215], v[120:123]
	v_mfma_f32_16x16x32_bf16 v[116:119], v[92:95], v[220:223], v[116:119]
	v_mfma_f32_16x16x32_bf16 v[112:115], v[162:165], v[220:223], v[112:115]
	v_mfma_f32_16x16x32_bf16 v[108:111], v[92:95], v[228:231], v[108:111]
	v_mfma_f32_16x16x32_bf16 v[104:107], v[162:165], v[228:231], v[104:107]
	v_mfma_f32_16x16x32_bf16 v[60:63], v[166:169], v[200:203], v[60:63]
	v_mfma_f32_16x16x32_bf16 v[56:59], v[192:195], v[200:203], v[56:59]
	v_mfma_f32_16x16x32_bf16 v[52:55], v[166:169], v[208:211], v[52:55]
	v_mfma_f32_16x16x32_bf16 v[48:51], v[192:195], v[208:211], v[48:51]
	v_mfma_f32_16x16x32_bf16 v[44:47], v[166:169], v[216:219], v[44:47]
	v_mfma_f32_16x16x32_bf16 v[40:43], v[192:195], v[216:219], v[40:43]
	v_mfma_f32_16x16x32_bf16 v[36:39], v[166:169], v[224:227], v[36:39]
	v_mfma_f32_16x16x32_bf16 v[32:35], v[192:195], v[224:227], v[32:35]
	v_mfma_f32_16x16x32_bf16 v[60:63], v[188:191], v[204:207], v[60:63]
	v_mfma_f32_16x16x32_bf16 v[56:59], v[196:199], v[204:207], v[56:59]
	v_mfma_f32_16x16x32_bf16 v[52:55], v[188:191], v[212:215], v[52:55]
	v_mfma_f32_16x16x32_bf16 v[48:51], v[196:199], v[212:215], v[48:51]
	v_mfma_f32_16x16x32_bf16 v[44:47], v[188:191], v[220:223], v[44:47]
	v_mfma_f32_16x16x32_bf16 v[40:43], v[196:199], v[220:223], v[40:43]
	v_mfma_f32_16x16x32_bf16 v[36:39], v[188:191], v[228:231], v[36:39]
	v_mfma_f32_16x16x32_bf16 v[32:35], v[196:199], v[228:231], v[32:35]
	s_barrier
	s_add_i32 s67, s67, s8
	v_lshl_add_u64 v[170:171], s[14:15], 0, v[140:141]
	s_mov_b32 m0, s67
	ds_read_b128 v[200:203], v187 offset:16384
	ds_read_b128 v[204:207], v187 offset:17408
	ds_read_b128 v[208:211], v187 offset:18432
	ds_read_b128 v[212:215], v187 offset:19456
	ds_read_b128 v[216:219], v187 offset:20480
	ds_read_b128 v[220:223], v187 offset:21504
	ds_read_b128 v[224:227], v187 offset:22528
	ds_read_b128 v[228:231], v187 offset:23552
	global_load_lds_dwordx4 v[170:171], off
	s_add_i32 m0, s67, 0x2000
	s_add_u32 s80, s14, 0x80000
	v_lshl_add_u64 v[232:233], s[14:15], 0, v[136:137]
	s_addc_u32 s81, s15, 0
	s_add_i32 s67, s82, s8
	global_load_lds_dwordx4 v[232:233], off
	v_lshl_add_u64 v[234:235], s[80:81], 0, v[140:141]
	s_mov_b32 m0, s67
	v_lshl_add_u64 v[236:237], s[16:17], 0, v[138:139]
	global_load_lds_dwordx4 v[234:235], off
	v_lshl_add_u64 v[234:235], s[80:81], 0, v[136:137]
	s_add_i32 m0, s67, 0x2000
	s_nop 0
	global_load_lds_dwordx4 v[234:235], off
	v_lshl_add_u64 v[234:235], s[16:17], 0, v[142:143]
	s_mov_b32 m0, s9
	s_nop 0
	global_load_lds_dwordx4 v[234:235], off
	s_mov_b32 m0, s35
	s_nop 0
	global_load_lds_dwordx4 v[236:237], off
	s_waitcnt vmcnt(8)
	s_waitcnt lgkmcnt(0)
	s_barrier
	s_waitcnt lgkmcnt(0)
	v_mfma_f32_16x16x32_bf16 v[100:103], v[88:91], v[200:203], v[100:103]
	v_mfma_f32_16x16x32_bf16 v[96:99], v[158:161], v[200:203], v[96:99]
	v_mfma_f32_16x16x32_bf16 v[84:87], v[88:91], v[208:211], v[84:87]
	v_mfma_f32_16x16x32_bf16 v[80:83], v[158:161], v[208:211], v[80:83]
	v_mfma_f32_16x16x32_bf16 v[76:79], v[88:91], v[216:219], v[76:79]
	v_mfma_f32_16x16x32_bf16 v[72:75], v[158:161], v[216:219], v[72:75]
	v_mfma_f32_16x16x32_bf16 v[68:71], v[88:91], v[224:227], v[68:71]
	v_mfma_f32_16x16x32_bf16 v[64:67], v[158:161], v[224:227], v[64:67]
	v_mfma_f32_16x16x32_bf16 v[100:103], v[92:95], v[204:207], v[100:103]
	v_mfma_f32_16x16x32_bf16 v[96:99], v[162:165], v[204:207], v[96:99]
	v_mfma_f32_16x16x32_bf16 v[84:87], v[92:95], v[212:215], v[84:87]
	v_mfma_f32_16x16x32_bf16 v[80:83], v[162:165], v[212:215], v[80:83]
	v_mfma_f32_16x16x32_bf16 v[76:79], v[92:95], v[220:223], v[76:79]
	v_mfma_f32_16x16x32_bf16 v[72:75], v[162:165], v[220:223], v[72:75]
	v_mfma_f32_16x16x32_bf16 v[68:71], v[92:95], v[228:231], v[68:71]
	v_mfma_f32_16x16x32_bf16 v[64:67], v[162:165], v[228:231], v[64:67]
	v_mfma_f32_16x16x32_bf16 v[28:31], v[166:169], v[200:203], v[28:31]
	v_mfma_f32_16x16x32_bf16 v[24:27], v[192:195], v[200:203], v[24:27]
	v_mfma_f32_16x16x32_bf16 v[20:23], v[166:169], v[208:211], v[20:23]
	v_mfma_f32_16x16x32_bf16 v[16:19], v[192:195], v[208:211], v[16:19]
	v_mfma_f32_16x16x32_bf16 v[12:15], v[166:169], v[216:219], v[12:15]
	v_mfma_f32_16x16x32_bf16 v[8:11], v[192:195], v[216:219], v[8:11]
	v_mfma_f32_16x16x32_bf16 v[4:7], v[166:169], v[224:227], v[4:7]
	v_mfma_f32_16x16x32_bf16 v[0:3], v[192:195], v[224:227], v[0:3]
	v_mfma_f32_16x16x32_bf16 v[28:31], v[188:191], v[204:207], v[28:31]
	v_mfma_f32_16x16x32_bf16 v[24:27], v[196:199], v[204:207], v[24:27]
	v_mfma_f32_16x16x32_bf16 v[20:23], v[188:191], v[212:215], v[20:23]
	v_mfma_f32_16x16x32_bf16 v[16:19], v[196:199], v[212:215], v[16:19]
	v_mfma_f32_16x16x32_bf16 v[12:15], v[188:191], v[220:223], v[12:15]
	v_mfma_f32_16x16x32_bf16 v[8:11], v[196:199], v[220:223], v[8:11]
	v_mfma_f32_16x16x32_bf16 v[4:7], v[188:191], v[228:231], v[4:7]
	v_mfma_f32_16x16x32_bf16 v[0:3], v[196:199], v[228:231], v[0:3]
	s_barrier
	s_add_i32 s67, 0, 0x18000
	v_add_u32_e32 v144, s67, v185
	s_add_i32 s80, 0, 0x1c000
	ds_read_b128 v[88:91], v144
	ds_read_b128 v[92:95], v144 offset:1024
	ds_read_b128 v[158:161], v144 offset:2048
	ds_read_b128 v[162:165], v144 offset:3072
	v_add_u32_e32 v144, s80, v185
	ds_read_b128 v[166:169], v144
	ds_read_b128 v[188:191], v144 offset:1024
	ds_read_b128 v[192:195], v144 offset:2048
	ds_read_b128 v[196:199], v144 offset:3072
	s_add_u32 s16, s16, 0x80000
	s_addc_u32 s17, s17, 0
	s_mov_b32 m0, s5
	v_lshl_add_u64 v[238:239], s[16:17], 0, v[142:143]
	ds_read_b128 v[200:203], v187 offset:32768
	ds_read_b128 v[204:207], v187 offset:33792
	ds_read_b128 v[208:211], v187 offset:34816
	ds_read_b128 v[212:215], v187 offset:35840
	ds_read_b128 v[216:219], v187 offset:36864
	ds_read_b128 v[220:223], v187 offset:37888
	ds_read_b128 v[224:227], v187 offset:38912
	ds_read_b128 v[228:231], v187 offset:39936
	global_load_lds_dwordx4 v[238:239], off
	v_lshl_add_u64 v[238:239], s[16:17], 0, v[138:139]
	s_mov_b32 m0, s26
	s_nop 0
	global_load_lds_dwordx4 v[238:239], off
	s_waitcnt vmcnt(8)
	s_waitcnt lgkmcnt(0)
	s_barrier
	s_waitcnt lgkmcnt(0)
	v_mfma_f32_16x16x32_bf16 v[132:135], v[88:91], v[200:203], v[132:135]
	v_mfma_f32_16x16x32_bf16 v[128:131], v[158:161], v[200:203], v[128:131]
	v_mfma_f32_16x16x32_bf16 v[124:127], v[88:91], v[208:211], v[124:127]
	v_mfma_f32_16x16x32_bf16 v[120:123], v[158:161], v[208:211], v[120:123]
	v_mfma_f32_16x16x32_bf16 v[116:119], v[88:91], v[216:219], v[116:119]
	v_mfma_f32_16x16x32_bf16 v[112:115], v[158:161], v[216:219], v[112:115]
	v_mfma_f32_16x16x32_bf16 v[108:111], v[88:91], v[224:227], v[108:111]
	v_mfma_f32_16x16x32_bf16 v[104:107], v[158:161], v[224:227], v[104:107]
	v_mfma_f32_16x16x32_bf16 v[132:135], v[92:95], v[204:207], v[132:135]
	v_mfma_f32_16x16x32_bf16 v[128:131], v[162:165], v[204:207], v[128:131]
	v_mfma_f32_16x16x32_bf16 v[124:127], v[92:95], v[212:215], v[124:127]
	v_mfma_f32_16x16x32_bf16 v[120:123], v[162:165], v[212:215], v[120:123]
	v_mfma_f32_16x16x32_bf16 v[116:119], v[92:95], v[220:223], v[116:119]
	v_mfma_f32_16x16x32_bf16 v[112:115], v[162:165], v[220:223], v[112:115]
	v_mfma_f32_16x16x32_bf16 v[108:111], v[92:95], v[228:231], v[108:111]
	v_mfma_f32_16x16x32_bf16 v[104:107], v[162:165], v[228:231], v[104:107]
	v_mfma_f32_16x16x32_bf16 v[60:63], v[166:169], v[200:203], v[60:63]
	v_mfma_f32_16x16x32_bf16 v[56:59], v[192:195], v[200:203], v[56:59]
	v_mfma_f32_16x16x32_bf16 v[52:55], v[166:169], v[208:211], v[52:55]
	v_mfma_f32_16x16x32_bf16 v[48:51], v[192:195], v[208:211], v[48:51]
	v_mfma_f32_16x16x32_bf16 v[44:47], v[166:169], v[216:219], v[44:47]
	v_mfma_f32_16x16x32_bf16 v[40:43], v[192:195], v[216:219], v[40:43]
	v_mfma_f32_16x16x32_bf16 v[36:39], v[166:169], v[224:227], v[36:39]
	v_mfma_f32_16x16x32_bf16 v[32:35], v[192:195], v[224:227], v[32:35]
	v_mfma_f32_16x16x32_bf16 v[60:63], v[188:191], v[204:207], v[60:63]
	v_mfma_f32_16x16x32_bf16 v[56:59], v[196:199], v[204:207], v[56:59]
	v_mfma_f32_16x16x32_bf16 v[52:55], v[188:191], v[212:215], v[52:55]
	v_mfma_f32_16x16x32_bf16 v[48:51], v[196:199], v[212:215], v[48:51]
	v_mfma_f32_16x16x32_bf16 v[44:47], v[188:191], v[220:223], v[44:47]
	v_mfma_f32_16x16x32_bf16 v[40:43], v[196:199], v[220:223], v[40:43]
	v_mfma_f32_16x16x32_bf16 v[36:39], v[188:191], v[228:231], v[36:39]
	v_mfma_f32_16x16x32_bf16 v[32:35], v[196:199], v[228:231], v[32:35]
	s_barrier
	s_add_i32 s16, s67, s8
	v_lshl_add_u64 v[170:171], v[170:171], 0, s[68:69]
	s_mov_b32 m0, s16
	ds_read_b128 v[200:203], v187 offset:49152
	ds_read_b128 v[204:207], v187 offset:50176
	ds_read_b128 v[208:211], v187 offset:51200
	ds_read_b128 v[212:215], v187 offset:52224
	ds_read_b128 v[216:219], v187 offset:53248
	ds_read_b128 v[220:223], v187 offset:54272
	ds_read_b128 v[224:227], v187 offset:55296
	ds_read_b128 v[228:231], v187 offset:56320
	global_load_lds_dwordx4 v[170:171], off
	s_add_i32 m0, s16, 0x2000
	s_add_u32 s14, s14, 0x80080
	v_lshl_add_u64 v[170:171], v[232:233], 0, s[68:69]
	s_addc_u32 s15, s15, 0
	s_add_i32 s16, s80, s8
	global_load_lds_dwordx4 v[170:171], off
	v_lshl_add_u64 v[170:171], s[14:15], 0, v[140:141]
	s_mov_b32 m0, s16
	s_nop 0
	global_load_lds_dwordx4 v[170:171], off
	v_lshl_add_u64 v[170:171], s[14:15], 0, v[136:137]
	s_add_i32 m0, s16, 0x2000
	s_nop 0
	global_load_lds_dwordx4 v[170:171], off
	v_lshl_add_u64 v[170:171], v[234:235], 0, s[68:69]
	s_mov_b32 m0, s4
	s_nop 0
	global_load_lds_dwordx4 v[170:171], off
	v_lshl_add_u64 v[170:171], v[236:237], 0, s[68:69]
	s_mov_b32 m0, s70
	s_nop 0
	global_load_lds_dwordx4 v[170:171], off
	s_waitcnt vmcnt(8)
	s_waitcnt lgkmcnt(0)
	s_barrier
	s_waitcnt lgkmcnt(0)
	v_mfma_f32_16x16x32_bf16 v[100:103], v[88:91], v[200:203], v[100:103]
	v_mfma_f32_16x16x32_bf16 v[96:99], v[158:161], v[200:203], v[96:99]
	v_mfma_f32_16x16x32_bf16 v[84:87], v[88:91], v[208:211], v[84:87]
	v_mfma_f32_16x16x32_bf16 v[80:83], v[158:161], v[208:211], v[80:83]
	v_mfma_f32_16x16x32_bf16 v[76:79], v[88:91], v[216:219], v[76:79]
	v_mfma_f32_16x16x32_bf16 v[72:75], v[158:161], v[216:219], v[72:75]
	v_mfma_f32_16x16x32_bf16 v[68:71], v[88:91], v[224:227], v[68:71]
	v_mfma_f32_16x16x32_bf16 v[64:67], v[158:161], v[224:227], v[64:67]
	v_mfma_f32_16x16x32_bf16 v[100:103], v[92:95], v[204:207], v[100:103]
	v_mfma_f32_16x16x32_bf16 v[96:99], v[162:165], v[204:207], v[96:99]
	v_mfma_f32_16x16x32_bf16 v[84:87], v[92:95], v[212:215], v[84:87]
	v_mfma_f32_16x16x32_bf16 v[80:83], v[162:165], v[212:215], v[80:83]
	v_mfma_f32_16x16x32_bf16 v[76:79], v[92:95], v[220:223], v[76:79]
	v_mfma_f32_16x16x32_bf16 v[72:75], v[162:165], v[220:223], v[72:75]
	v_mfma_f32_16x16x32_bf16 v[68:71], v[92:95], v[228:231], v[68:71]
	v_mfma_f32_16x16x32_bf16 v[64:67], v[162:165], v[228:231], v[64:67]
	v_mfma_f32_16x16x32_bf16 v[28:31], v[166:169], v[200:203], v[28:31]
	v_mfma_f32_16x16x32_bf16 v[24:27], v[192:195], v[200:203], v[24:27]
	v_mfma_f32_16x16x32_bf16 v[20:23], v[166:169], v[208:211], v[20:23]
	v_mfma_f32_16x16x32_bf16 v[16:19], v[192:195], v[208:211], v[16:19]
	v_mfma_f32_16x16x32_bf16 v[12:15], v[166:169], v[216:219], v[12:15]
	v_mfma_f32_16x16x32_bf16 v[8:11], v[192:195], v[216:219], v[8:11]
	v_mfma_f32_16x16x32_bf16 v[4:7], v[166:169], v[224:227], v[4:7]
	v_mfma_f32_16x16x32_bf16 v[0:3], v[192:195], v[224:227], v[0:3]
	v_mfma_f32_16x16x32_bf16 v[28:31], v[188:191], v[204:207], v[28:31]
	v_mfma_f32_16x16x32_bf16 v[24:27], v[196:199], v[204:207], v[24:27]
	v_mfma_f32_16x16x32_bf16 v[20:23], v[188:191], v[212:215], v[20:23]
	v_mfma_f32_16x16x32_bf16 v[16:19], v[196:199], v[212:215], v[16:19]
	v_mfma_f32_16x16x32_bf16 v[12:15], v[188:191], v[220:223], v[12:15]
	v_mfma_f32_16x16x32_bf16 v[8:11], v[196:199], v[220:223], v[8:11]
	v_mfma_f32_16x16x32_bf16 v[4:7], v[188:191], v[228:231], v[4:7]
	v_mfma_f32_16x16x32_bf16 v[0:3], v[196:199], v[228:231], v[0:3]
	s_barrier
	s_add_i32 s53, s53, 2
	s_add_u32 s12, s12, 0x100
	s_addc_u32 s13, s13, 0
	s_add_u32 s49, s49, 0x100
	s_addc_u32 s52, s52, 0
	s_cmp_gt_u32 s53, 29
	s_cbranch_scc0 .LBB0_215
	s_and_b64 vcc, exec, s[28:29]
	s_cbranch_vccz .LBB0_218
	s_barrier

.LBB0_385:
	s_setprio 0
	v_readlane_b32 s26, v240, 29
	v_readlane_b32 s27, v240, 30
	s_mov_b64 s[12:13], s[26:27]
	s_getreg_b32 s0, hwreg(HW_REG_XCC_ID, 0, 4)
	s_waitcnt vmcnt(0)
	s_barrier
	s_mov_b64 s[10:11], exec
	v_readlane_b32 s4, v241, 2
	v_readlane_b32 s5, v241, 3
	s_and_b64 s[4:5], s[10:11], s[4:5]
	s_mov_b64 exec, s[4:5]
	s_cbranch_execz .LBB0_437
	v_readlane_b32 s1, v240, 13
	s_load_dwordx2 s[12:13], s[12:13], 0xa8
	s_waitcnt vmcnt(0) expcnt(0) lgkmcnt(0)
	v_mov_b32_e32 v0, s1
	ds_read_b32 v2, v0
	v_readlane_b32 s1, v240, 14
	s_and_b32 s0, s0, 15
	s_waitcnt lgkmcnt(0)
	v_cmp_ne_u32_e32 vcc, 0, v2
	v_mov_b32_e32 v0, s1
	ds_read_b32 v0, v0
	s_cbranch_vccnz .LBB0_401
	s_add_u32 s14, s12, 0x1000
	s_addc_u32 s15, s13, 0
	s_add_u32 s16, s12, 0x1100
	s_addc_u32 s17, s13, 0
	s_add_u32 s18, s12, 0x1200
	s_addc_u32 s19, s13, 0
	s_add_u32 s20, s12, 0x1300
	s_addc_u32 s21, s13, 0
	s_mov_b32 s1, 1
	s_branch .LBB0_389

.LBB0_778:
	s_mul_hi_u32 s0, s60, 0xf9824000
	s_sub_i32 s53, s0, s60
	v_readlane_b32 s0, v241, 52
	v_readlane_b32 s1, v241, 53
	v_mov_b32_e32 v14, v172
	s_mul_i32 s52, s60, 0xf9824000
	v_cndmask_b32_e64 v0, 0, 1, s[0:1]
	v_cmp_ne_u32_e64 s[10:11], 1, v0
	s_andn2_b64 vcc, exec, s[0:1]
	v_readfirstlane_b32 s0, v14
	s_cbranch_vccnz .LBB0_861
	v_lshlrev_b32_e32 v0, 4, v14
	v_add_u32_e32 v1, 0x2000, v0
	v_ashrrev_i32_e32 v2, 31, v1
	v_lshrrev_b32_e32 v2, 22, v2
	v_add_u32_e32 v2, v1, v2
	v_ashrrev_i32_e32 v8, 10, v2
	v_mul_i32_i24_e32 v2, 0x400, v8
	s_ashr_i32 s24, s0, 6
	v_sub_u32_e32 v1, v1, v2
	s_ashr_i32 s1, s0, 8
	s_lshl_b32 s4, s24, 10
	v_lshrrev_b32_e32 v2, 4, v1
	s_waitcnt lgkmcnt(0)
	s_add_u32 s28, s12, 0xd400000
	v_bitop3_b32 v1, v2, v1, 32 bitop3:0x6c
	s_addc_u32 s29, s13, 0
	v_readlane_b32 s5, v240, 37
	v_ashrrev_i32_e32 v2, 31, v1
	s_add_u32 s27, s12, s5
	v_lshrrev_b32_e32 v2, 26, v2
	s_addc_u32 s35, s13, 0
	v_add_u32_e32 v2, v1, v2
	v_lshlrev_b32_e32 v3, 3, v8
	s_add_u32 s30, s27, 0x2200000
	v_ashrrev_i32_e32 v9, 6, v2
	v_and_b32_e32 v3, -16, v3
	s_addc_u32 s31, s35, 0
	v_readlane_b32 s5, v241, 56
	v_add_u32_e32 v3, v9, v3
	s_add_u32 s20, s30, s5
	v_and_b32_e32 v4, 3, v9
	s_mov_b32 s5, 0xfffe0
	v_lshrrev_b32_e32 v5, 2, v3
	v_lshlrev_b32_e32 v6, 1, v3
	v_and_b32_e32 v2, 0xc0, v2
	v_and_or_b32 v4, v3, s5, v4
	v_and_b32_e32 v5, 4, v5
	v_and_b32_e32 v6, 24, v6
	v_sub_u32_e32 v1, v1, v2
	v_or3_b32 v4, v4, v5, v6
	v_lshlrev_b32_e32 v5, 5, v8
	v_ashrrev_i16_sdwa v1, v180, sext(v1) dst_sel:DWORD dst_unused:UNUSED_PAD src0_sel:DWORD src1_sel:BYTE_0
	v_and_b32_e32 v5, 32, v5
	v_bfe_i32 v10, v1, 0, 16
	v_add_lshl_u32 v1, v5, v10, 1
	v_lshl_add_u32 v152, v4, 12, v1
	v_lshl_add_u32 v154, v3, 12, v1
	v_bfe_i32 v1, v14, 27, 1
	v_lshrrev_b32_e32 v1, 22, v1
	v_add_u32_e32 v1, v0, v1
	v_and_b32_e32 v1, 0xfffffc00, v1
	v_sub_u32_e32 v0, v0, v1
	v_lshrrev_b32_e32 v1, 4, v0
	v_ashrrev_i32_e32 v2, 31, v14
	v_bitop3_b32 v0, v1, v0, 32 bitop3:0x6c
	v_lshrrev_b32_e32 v2, 26, v2
	v_ashrrev_i32_e32 v1, 31, v0
	v_add_u32_e32 v2, v14, v2
	v_lshrrev_b32_e32 v1, 26, v1
	v_ashrrev_i32_e32 v12, 6, v2
	v_add_u32_e32 v1, v0, v1
	v_lshlrev_b32_e32 v2, 3, v12
	s_addc_u32 s21, s31, 0
	v_ashrrev_i32_e32 v11, 6, v1
	v_and_b32_e32 v2, -16, v2
	s_add_u32 s8, s20, 0x80000
	v_add_u32_e32 v2, v11, v2
	s_addc_u32 s9, s21, 0
	v_readlane_b32 s14, v241, 54
	v_and_b32_e32 v3, 3, v11
	v_lshrrev_b32_e32 v4, 2, v2
	v_lshlrev_b32_e32 v5, 1, v2
	v_and_b32_e32 v1, 0xc0, v1
	v_readlane_b32 s15, v241, 55
	s_add_u32 s18, s28, s14
	v_and_or_b32 v3, v2, s5, v3
	v_and_b32_e32 v4, 4, v4
	v_and_b32_e32 v5, 24, v5
	v_sub_u32_e32 v0, v0, v1
	s_addc_u32 s19, s29, s15
	v_or3_b32 v3, v3, v4, v5
	v_lshlrev_b32_e32 v4, 5, v12
	v_ashrrev_i16_sdwa v0, v180, sext(v0) dst_sel:DWORD dst_unused:UNUSED_PAD src0_sel:DWORD src1_sel:BYTE_0
	s_add_u32 s14, s18, 0x80000
	v_and_b32_e32 v4, 32, v4
	v_bfe_i32 v13, v0, 0, 16
	s_addc_u32 s15, s19, 0
	v_add_lshl_u32 v0, v4, v13, 1
	s_add_i32 s5, s4, 0
	v_lshl_add_u32 v156, v3, 12, v0
	s_add_i32 m0, s5, 0x10000
	v_lshl_add_u32 v158, v2, 12, v0
	global_load_lds_dwordx4 v156, s[20:21]
	s_add_i32 m0, s5, 0x12000
	s_add_i32 s26, s5, 0x6000
	global_load_lds_dwordx4 v152, s[20:21]
	s_add_i32 m0, s5, 0x14000
	v_mov_b32_e32 v157, v145
	global_load_lds_dwordx4 v156, s[8:9]
	s_add_i32 m0, s5, 0x16000
	v_mov_b32_e32 v153, v145
	global_load_lds_dwordx4 v152, s[8:9]
	s_mov_b32 m0, s5
	s_add_i32 s8, s5, 0x2000
	global_load_lds_dwordx4 v158, s[18:19]
	s_mov_b32 m0, s8
	s_add_i32 s9, s5, 0x4000
	global_load_lds_dwordx4 v154, s[18:19]
	s_mov_b32 m0, s9
	v_mov_b32_e32 v159, v145
	global_load_lds_dwordx4 v158, s[14:15]
	s_mov_b32 m0, s26
	v_mov_b32_e32 v155, v145
	global_load_lds_dwordx4 v154, s[14:15]
	s_cmp_eq_u32 s1, 1
	v_lshl_add_u64 v[6:7], s[20:21], 0, v[156:157]
	v_lshl_add_u64 v[4:5], s[20:21], 0, v[152:153]
	v_lshl_add_u64 v[0:1], s[18:19], 0, v[158:159]
	s_cselect_b64 s[22:23], -1, 0
	s_cmp_lg_u32 s1, 1
	v_lshl_add_u64 v[2:3], s[18:19], 0, v[154:155]
	s_cbranch_scc1 .LBB0_781
	s_barrier
	s_setprio 1

.LBB0_785:
	s_add_u32 s14, s12, 0xfff80080
	s_addc_u32 s15, s13, -1
	s_add_i32 s86, 0, 0x10000
	s_cmp_eq_u32 s1, s85
	s_cselect_b32 s51, s47, s15
	s_cselect_b32 s50, s67, s14
	s_cselect_b32 s15, s80, s84
	s_cselect_b32 s14, s81, s83
	s_add_i32 s96, 0, 0x14000
	v_add_u32_e32 v140, s86, v186
	v_add_u32_e32 v144, s96, v186
	ds_read_b128 v[128:131], v140
	ds_read_b128 v[132:135], v140 offset:1024
	ds_read_b128 v[136:139], v140 offset:2048
	ds_read_b128 v[140:143], v140 offset:3072
	ds_read_b128 v[164:167], v144
	ds_read_b128 v[168:171], v144 offset:1024
	ds_read_b128 v[190:193], v144 offset:2048
	ds_read_b128 v[194:197], v144 offset:3072
	v_lshl_add_u64 v[230:231], s[12:13], 0, v[160:161]
	s_add_i32 m0, s5, 0xc000
	ds_read_b128 v[198:201], v188
	ds_read_b128 v[202:205], v188 offset:1024
	ds_read_b128 v[206:209], v188 offset:2048
	ds_read_b128 v[210:213], v188 offset:3072
	ds_read_b128 v[214:217], v188 offset:4096
	ds_read_b128 v[218:221], v188 offset:5120
	ds_read_b128 v[222:225], v188 offset:6144
	ds_read_b128 v[226:229], v188 offset:7168
	global_load_lds_dwordx4 v[230:231], off
	v_lshl_add_u64 v[230:231], s[12:13], 0, v[162:163]
	s_add_i32 m0, s5, 0xe000
	s_nop 0
	global_load_lds_dwordx4 v[230:231], off
	s_waitcnt vmcnt(8)
	s_waitcnt lgkmcnt(0)
	s_barrier
	s_waitcnt lgkmcnt(0)
	v_mfma_f32_16x16x32_bf16 v[124:127], v[128:131], v[198:201], v[124:127]
	v_mfma_f32_16x16x32_bf16 v[120:123], v[136:139], v[198:201], v[120:123]
	v_mfma_f32_16x16x32_bf16 v[116:119], v[128:131], v[206:209], v[116:119]
	v_mfma_f32_16x16x32_bf16 v[112:115], v[136:139], v[206:209], v[112:115]
	v_mfma_f32_16x16x32_bf16 v[108:111], v[128:131], v[214:217], v[108:111]
	v_mfma_f32_16x16x32_bf16 v[104:107], v[136:139], v[214:217], v[104:107]
	v_mfma_f32_16x16x32_bf16 v[100:103], v[128:131], v[222:225], v[100:103]
	v_mfma_f32_16x16x32_bf16 v[96:99], v[136:139], v[222:225], v[96:99]
	v_mfma_f32_16x16x32_bf16 v[124:127], v[132:135], v[202:205], v[124:127]
	v_mfma_f32_16x16x32_bf16 v[120:123], v[140:143], v[202:205], v[120:123]
	v_mfma_f32_16x16x32_bf16 v[116:119], v[132:135], v[210:213], v[116:119]
	v_mfma_f32_16x16x32_bf16 v[112:115], v[140:143], v[210:213], v[112:115]
	v_mfma_f32_16x16x32_bf16 v[108:111], v[132:135], v[218:221], v[108:111]
	v_mfma_f32_16x16x32_bf16 v[104:107], v[140:143], v[218:221], v[104:107]
	v_mfma_f32_16x16x32_bf16 v[100:103], v[132:135], v[226:229], v[100:103]
	v_mfma_f32_16x16x32_bf16 v[96:99], v[140:143], v[226:229], v[96:99]
	v_mfma_f32_16x16x32_bf16 v[60:63], v[164:167], v[198:201], v[60:63]
	v_mfma_f32_16x16x32_bf16 v[56:59], v[190:193], v[198:201], v[56:59]
	v_mfma_f32_16x16x32_bf16 v[52:55], v[164:167], v[206:209], v[52:55]
	v_mfma_f32_16x16x32_bf16 v[48:51], v[190:193], v[206:209], v[48:51]
	v_mfma_f32_16x16x32_bf16 v[44:47], v[164:167], v[214:217], v[44:47]
	v_mfma_f32_16x16x32_bf16 v[40:43], v[190:193], v[214:217], v[40:43]
	v_mfma_f32_16x16x32_bf16 v[36:39], v[164:167], v[222:225], v[36:39]
	v_mfma_f32_16x16x32_bf16 v[32:35], v[190:193], v[222:225], v[32:35]
	v_mfma_f32_16x16x32_bf16 v[60:63], v[168:171], v[202:205], v[60:63]
	v_mfma_f32_16x16x32_bf16 v[56:59], v[194:197], v[202:205], v[56:59]
	v_mfma_f32_16x16x32_bf16 v[52:55], v[168:171], v[210:213], v[52:55]
	v_mfma_f32_16x16x32_bf16 v[48:51], v[194:197], v[210:213], v[48:51]
	v_mfma_f32_16x16x32_bf16 v[44:47], v[168:171], v[218:221], v[44:47]
	v_mfma_f32_16x16x32_bf16 v[40:43], v[194:197], v[218:221], v[40:43]
	v_mfma_f32_16x16x32_bf16 v[36:39], v[168:171], v[226:229], v[36:39]
	v_mfma_f32_16x16x32_bf16 v[32:35], v[194:197], v[226:229], v[32:35]
	s_barrier
	s_add_i32 s86, s86, s4
	v_lshl_add_u64 v[230:231], s[14:15], 0, v[156:157]
	s_mov_b32 m0, s86
	ds_read_b128 v[198:201], v188 offset:16384
	ds_read_b128 v[202:205], v188 offset:17408
	ds_read_b128 v[206:209], v188 offset:18432
	ds_read_b128 v[210:213], v188 offset:19456
	ds_read_b128 v[214:217], v188 offset:20480
	ds_read_b128 v[218:221], v188 offset:21504
	ds_read_b128 v[222:225], v188 offset:22528
	ds_read_b128 v[226:229], v188 offset:23552
	global_load_lds_dwordx4 v[230:231], off
	s_add_i32 m0, s86, 0x2000
	s_add_u32 s86, s14, 0x80000
	v_lshl_add_u64 v[232:233], s[14:15], 0, v[152:153]
	s_addc_u32 s87, s15, 0
	s_add_i32 s96, s96, s4
	global_load_lds_dwordx4 v[232:233], off
	v_lshl_add_u64 v[234:235], s[86:87], 0, v[156:157]
	s_mov_b32 m0, s96
	v_lshl_add_u64 v[236:237], s[50:51], 0, v[154:155]
	global_load_lds_dwordx4 v[234:235], off
	v_lshl_add_u64 v[234:235], s[86:87], 0, v[152:153]
	s_add_i32 m0, s96, 0x2000
	s_nop 0
	global_load_lds_dwordx4 v[234:235], off
	v_lshl_add_u64 v[234:235], s[50:51], 0, v[158:159]
	s_mov_b32 m0, s5
	s_nop 0
	global_load_lds_dwordx4 v[234:235], off
	s_mov_b32 m0, s8
	s_nop 0
	global_load_lds_dwordx4 v[236:237], off
	s_waitcnt vmcnt(8)
	s_waitcnt lgkmcnt(0)
	s_barrier
	s_waitcnt lgkmcnt(0)
	v_mfma_f32_16x16x32_bf16 v[92:95], v[128:131], v[198:201], v[92:95]
	v_mfma_f32_16x16x32_bf16 v[88:91], v[136:139], v[198:201], v[88:91]
	v_mfma_f32_16x16x32_bf16 v[84:87], v[128:131], v[206:209], v[84:87]
	v_mfma_f32_16x16x32_bf16 v[80:83], v[136:139], v[206:209], v[80:83]
	v_mfma_f32_16x16x32_bf16 v[76:79], v[128:131], v[214:217], v[76:79]
	v_mfma_f32_16x16x32_bf16 v[72:75], v[136:139], v[214:217], v[72:75]
	v_mfma_f32_16x16x32_bf16 v[68:71], v[128:131], v[222:225], v[68:71]
	v_mfma_f32_16x16x32_bf16 v[64:67], v[136:139], v[222:225], v[64:67]
	v_mfma_f32_16x16x32_bf16 v[92:95], v[132:135], v[202:205], v[92:95]
	v_mfma_f32_16x16x32_bf16 v[88:91], v[140:143], v[202:205], v[88:91]
	v_mfma_f32_16x16x32_bf16 v[84:87], v[132:135], v[210:213], v[84:87]
	v_mfma_f32_16x16x32_bf16 v[80:83], v[140:143], v[210:213], v[80:83]
	v_mfma_f32_16x16x32_bf16 v[76:79], v[132:135], v[218:221], v[76:79]
	v_mfma_f32_16x16x32_bf16 v[72:75], v[140:143], v[218:221], v[72:75]
	v_mfma_f32_16x16x32_bf16 v[68:71], v[132:135], v[226:229], v[68:71]
	v_mfma_f32_16x16x32_bf16 v[64:67], v[140:143], v[226:229], v[64:67]
	v_mfma_f32_16x16x32_bf16 v[28:31], v[164:167], v[198:201], v[28:31]
	v_mfma_f32_16x16x32_bf16 v[24:27], v[190:193], v[198:201], v[24:27]
	v_mfma_f32_16x16x32_bf16 v[20:23], v[164:167], v[206:209], v[20:23]
	v_mfma_f32_16x16x32_bf16 v[16:19], v[190:193], v[206:209], v[16:19]
	v_mfma_f32_16x16x32_bf16 v[12:15], v[164:167], v[214:217], v[12:15]
	v_mfma_f32_16x16x32_bf16 v[8:11], v[190:193], v[214:217], v[8:11]
	v_mfma_f32_16x16x32_bf16 v[4:7], v[164:167], v[222:225], v[4:7]
	v_mfma_f32_16x16x32_bf16 v[0:3], v[190:193], v[222:225], v[0:3]
	v_mfma_f32_16x16x32_bf16 v[28:31], v[168:171], v[202:205], v[28:31]
	v_mfma_f32_16x16x32_bf16 v[24:27], v[194:197], v[202:205], v[24:27]
	v_mfma_f32_16x16x32_bf16 v[20:23], v[168:171], v[210:213], v[20:23]
	v_mfma_f32_16x16x32_bf16 v[16:19], v[194:197], v[210:213], v[16:19]
	v_mfma_f32_16x16x32_bf16 v[12:15], v[168:171], v[218:221], v[12:15]
	v_mfma_f32_16x16x32_bf16 v[8:11], v[194:197], v[218:221], v[8:11]
	v_mfma_f32_16x16x32_bf16 v[4:7], v[168:171], v[226:229], v[4:7]
	v_mfma_f32_16x16x32_bf16 v[0:3], v[194:197], v[226:229], v[0:3]
	s_barrier
	s_add_i32 s86, 0, 0x18000
	s_add_i32 s87, 0, 0x1c000
	v_add_u32_e32 v140, s86, v186
	v_add_u32_e32 v144, s87, v186
	ds_read_b128 v[128:131], v140
	ds_read_b128 v[132:135], v140 offset:1024
	ds_read_b128 v[136:139], v140 offset:2048
	ds_read_b128 v[140:143], v140 offset:3072
	ds_read_b128 v[164:167], v144
	ds_read_b128 v[168:171], v144 offset:1024
	ds_read_b128 v[190:193], v144 offset:2048
	ds_read_b128 v[194:197], v144 offset:3072
	s_add_u32 s50, s50, 0x80000
	s_addc_u32 s51, s51, 0
	s_mov_b32 m0, s9
	v_lshl_add_u64 v[238:239], s[50:51], 0, v[158:159]
	ds_read_b128 v[198:201], v188 offset:32768
	ds_read_b128 v[202:205], v188 offset:33792
	ds_read_b128 v[206:209], v188 offset:34816
	ds_read_b128 v[210:213], v188 offset:35840
	ds_read_b128 v[214:217], v188 offset:36864
	ds_read_b128 v[218:221], v188 offset:37888
	ds_read_b128 v[222:225], v188 offset:38912
	ds_read_b128 v[226:229], v188 offset:39936
	global_load_lds_dwordx4 v[238:239], off
	v_lshl_add_u64 v[238:239], s[50:51], 0, v[154:155]
	s_mov_b32 m0, s26
	s_nop 0
	global_load_lds_dwordx4 v[238:239], off
	s_waitcnt vmcnt(8)
	s_waitcnt lgkmcnt(0)
	s_barrier
	s_waitcnt lgkmcnt(0)
	v_mfma_f32_16x16x32_bf16 v[124:127], v[128:131], v[198:201], v[124:127]
	v_mfma_f32_16x16x32_bf16 v[120:123], v[136:139], v[198:201], v[120:123]
	v_mfma_f32_16x16x32_bf16 v[116:119], v[128:131], v[206:209], v[116:119]
	v_mfma_f32_16x16x32_bf16 v[112:115], v[136:139], v[206:209], v[112:115]
	v_mfma_f32_16x16x32_bf16 v[108:111], v[128:131], v[214:217], v[108:111]
	v_mfma_f32_16x16x32_bf16 v[104:107], v[136:139], v[214:217], v[104:107]
	v_mfma_f32_16x16x32_bf16 v[100:103], v[128:131], v[222:225], v[100:103]
	v_mfma_f32_16x16x32_bf16 v[96:99], v[136:139], v[222:225], v[96:99]
	v_mfma_f32_16x16x32_bf16 v[124:127], v[132:135], v[202:205], v[124:127]
	v_mfma_f32_16x16x32_bf16 v[120:123], v[140:143], v[202:205], v[120:123]
	v_mfma_f32_16x16x32_bf16 v[116:119], v[132:135], v[210:213], v[116:119]
	v_mfma_f32_16x16x32_bf16 v[112:115], v[140:143], v[210:213], v[112:115]
	v_mfma_f32_16x16x32_bf16 v[108:111], v[132:135], v[218:221], v[108:111]
	v_mfma_f32_16x16x32_bf16 v[104:107], v[140:143], v[218:221], v[104:107]
	v_mfma_f32_16x16x32_bf16 v[100:103], v[132:135], v[226:229], v[100:103]
	v_mfma_f32_16x16x32_bf16 v[96:99], v[140:143], v[226:229], v[96:99]
	v_mfma_f32_16x16x32_bf16 v[60:63], v[164:167], v[198:201], v[60:63]
	v_mfma_f32_16x16x32_bf16 v[56:59], v[190:193], v[198:201], v[56:59]
	v_mfma_f32_16x16x32_bf16 v[52:55], v[164:167], v[206:209], v[52:55]
	v_mfma_f32_16x16x32_bf16 v[48:51], v[190:193], v[206:209], v[48:51]
	v_mfma_f32_16x16x32_bf16 v[44:47], v[164:167], v[214:217], v[44:47]
	v_mfma_f32_16x16x32_bf16 v[40:43], v[190:193], v[214:217], v[40:43]
	v_mfma_f32_16x16x32_bf16 v[36:39], v[164:167], v[222:225], v[36:39]
	v_mfma_f32_16x16x32_bf16 v[32:35], v[190:193], v[222:225], v[32:35]
	v_mfma_f32_16x16x32_bf16 v[60:63], v[168:171], v[202:205], v[60:63]
	v_mfma_f32_16x16x32_bf16 v[56:59], v[194:197], v[202:205], v[56:59]
	v_mfma_f32_16x16x32_bf16 v[52:55], v[168:171], v[210:213], v[52:55]
	v_mfma_f32_16x16x32_bf16 v[48:51], v[194:197], v[210:213], v[48:51]
	v_mfma_f32_16x16x32_bf16 v[44:47], v[168:171], v[218:221], v[44:47]
	v_mfma_f32_16x16x32_bf16 v[40:43], v[194:197], v[218:221], v[40:43]
	v_mfma_f32_16x16x32_bf16 v[36:39], v[168:171], v[226:229], v[36:39]
	v_mfma_f32_16x16x32_bf16 v[32:35], v[194:197], v[226:229], v[32:35]
	s_barrier
	s_add_i32 s50, s86, s4
	v_lshl_add_u64 v[230:231], v[230:231], 0, s[68:69]
	s_mov_b32 m0, s50
	ds_read_b128 v[198:201], v188 offset:49152
	ds_read_b128 v[202:205], v188 offset:50176
	ds_read_b128 v[206:209], v188 offset:51200
	ds_read_b128 v[210:213], v188 offset:52224
	ds_read_b128 v[214:217], v188 offset:53248
	ds_read_b128 v[218:221], v188 offset:54272
	ds_read_b128 v[222:225], v188 offset:55296
	ds_read_b128 v[226:229], v188 offset:56320
	global_load_lds_dwordx4 v[230:231], off
	s_add_i32 m0, s50, 0x2000
	s_add_u32 s14, s14, 0x80080
	v_lshl_add_u64 v[230:231], v[232:233], 0, s[68:69]
	s_addc_u32 s15, s15, 0
	s_add_i32 s50, s87, s4
	global_load_lds_dwordx4 v[230:231], off
	v_lshl_add_u64 v[230:231], s[14:15], 0, v[156:157]
	s_mov_b32 m0, s50
	s_nop 0
	global_load_lds_dwordx4 v[230:231], off
	v_lshl_add_u64 v[230:231], s[14:15], 0, v[152:153]
	s_add_i32 m0, s50, 0x2000
	s_nop 0
	global_load_lds_dwordx4 v[230:231], off
	v_lshl_add_u64 v[230:231], v[234:235], 0, s[68:69]
	s_mov_b32 m0, s70
	s_nop 0
	global_load_lds_dwordx4 v[230:231], off
	v_lshl_add_u64 v[230:231], v[236:237], 0, s[68:69]
	s_mov_b32 m0, s76
	s_nop 0
	global_load_lds_dwordx4 v[230:231], off
	s_waitcnt vmcnt(8)
	s_waitcnt lgkmcnt(0)
	s_barrier
	s_waitcnt lgkmcnt(0)
	v_mfma_f32_16x16x32_bf16 v[92:95], v[128:131], v[198:201], v[92:95]
	v_mfma_f32_16x16x32_bf16 v[88:91], v[136:139], v[198:201], v[88:91]
	v_mfma_f32_16x16x32_bf16 v[84:87], v[128:131], v[206:209], v[84:87]
	v_mfma_f32_16x16x32_bf16 v[80:83], v[136:139], v[206:209], v[80:83]
	v_mfma_f32_16x16x32_bf16 v[76:79], v[128:131], v[214:217], v[76:79]
	v_mfma_f32_16x16x32_bf16 v[72:75], v[136:139], v[214:217], v[72:75]
	v_mfma_f32_16x16x32_bf16 v[68:71], v[128:131], v[222:225], v[68:71]
	v_mfma_f32_16x16x32_bf16 v[64:67], v[136:139], v[222:225], v[64:67]
	v_mfma_f32_16x16x32_bf16 v[92:95], v[132:135], v[202:205], v[92:95]
	v_mfma_f32_16x16x32_bf16 v[88:91], v[140:143], v[202:205], v[88:91]
	v_mfma_f32_16x16x32_bf16 v[84:87], v[132:135], v[210:213], v[84:87]
	v_mfma_f32_16x16x32_bf16 v[80:83], v[140:143], v[210:213], v[80:83]
	v_mfma_f32_16x16x32_bf16 v[76:79], v[132:135], v[218:221], v[76:79]
	v_mfma_f32_16x16x32_bf16 v[72:75], v[140:143], v[218:221], v[72:75]
	v_mfma_f32_16x16x32_bf16 v[68:71], v[132:135], v[226:229], v[68:71]
	v_mfma_f32_16x16x32_bf16 v[64:67], v[140:143], v[226:229], v[64:67]
	v_mfma_f32_16x16x32_bf16 v[28:31], v[164:167], v[198:201], v[28:31]
	v_mfma_f32_16x16x32_bf16 v[24:27], v[190:193], v[198:201], v[24:27]
	v_mfma_f32_16x16x32_bf16 v[20:23], v[164:167], v[206:209], v[20:23]
	v_mfma_f32_16x16x32_bf16 v[16:19], v[190:193], v[206:209], v[16:19]
	v_mfma_f32_16x16x32_bf16 v[12:15], v[164:167], v[214:217], v[12:15]
	v_mfma_f32_16x16x32_bf16 v[8:11], v[190:193], v[214:217], v[8:11]
	v_mfma_f32_16x16x32_bf16 v[4:7], v[164:167], v[222:225], v[4:7]
	v_mfma_f32_16x16x32_bf16 v[0:3], v[190:193], v[222:225], v[0:3]
	v_mfma_f32_16x16x32_bf16 v[28:31], v[168:171], v[202:205], v[28:31]
	v_mfma_f32_16x16x32_bf16 v[24:27], v[194:197], v[202:205], v[24:27]
	v_mfma_f32_16x16x32_bf16 v[20:23], v[168:171], v[210:213], v[20:23]
	v_mfma_f32_16x16x32_bf16 v[16:19], v[194:197], v[210:213], v[16:19]
	v_mfma_f32_16x16x32_bf16 v[12:15], v[168:171], v[218:221], v[12:15]
	v_mfma_f32_16x16x32_bf16 v[8:11], v[194:197], v[218:221], v[8:11]
	v_mfma_f32_16x16x32_bf16 v[4:7], v[168:171], v[226:229], v[4:7]
	v_mfma_f32_16x16x32_bf16 v[0:3], v[194:197], v[226:229], v[0:3]
	s_barrier
	s_add_i32 s14, s85, 2
	s_add_u32 s12, s12, 0x100
	s_addc_u32 s13, s13, 0
	s_add_u32 s83, s83, 0x100
	s_addc_u32 s84, s84, 0
	s_cmp_ge_u32 s85, s1
	s_mov_b32 s85, s14
	s_cbranch_scc0 .LBB0_785
	s_and_b64 vcc, exec, s[28:29]
	s_cbranch_vccz .LBB0_788
	s_barrier

.LBB0_861:
	s_setprio 0
	s_waitcnt lgkmcnt(0)
	s_mov_b64 s[12:13], s[76:77]
	s_getreg_b32 s0, hwreg(HW_REG_XCC_ID, 0, 4)
	s_waitcnt vmcnt(0)
	s_waitcnt vmcnt(0)
	s_barrier
	s_mov_b64 s[6:7], exec
	v_readlane_b32 s4, v241, 2
	v_readlane_b32 s5, v241, 3
	s_and_b64 s[4:5], s[6:7], s[4:5]
	s_mov_b64 exec, s[4:5]
	s_cbranch_execz .LBB0_913
	v_readlane_b32 s1, v240, 13
	s_load_dwordx2 s[12:13], s[12:13], 0xa8
	s_waitcnt vmcnt(0) expcnt(0) lgkmcnt(0)
	v_mov_b32_e32 v0, s1
	ds_read_b32 v2, v0
	v_readlane_b32 s1, v240, 14
	s_and_b32 s0, s0, 15
	s_waitcnt lgkmcnt(0)
	v_cmp_ne_u32_e32 vcc, 0, v2
	v_mov_b32_e32 v0, s1
	ds_read_b32 v0, v0
	s_cbranch_vccnz .LBB0_877
	s_add_u32 s14, s12, 0x1000
	s_addc_u32 s15, s13, 0
	s_add_u32 s16, s12, 0x1100
	s_addc_u32 s17, s13, 0
	s_add_u32 s18, s12, 0x1200
	s_addc_u32 s19, s13, 0
	s_add_u32 s20, s12, 0x1300
	s_addc_u32 s21, s13, 0
	s_mov_b32 s1, 1
	s_branch .LBB0_865

.LBB0_982:
	s_or_b64 exec, exec, s[6:7]
	v_readlane_b32 s0, v240, 38
	s_mov_b64 s[6:7], s[76:77]
	v_mov_b32_e32 v14, v172
	v_readlane_b32 s1, v240, 39
	s_waitcnt lgkmcnt(0)
	s_barrier
	s_and_b64 vcc, exec, s[0:1]
	v_readfirstlane_b32 s0, v14
	s_cbranch_vccnz .LBB0_998
	v_lshlrev_b32_e32 v0, 4, v14
	v_add_u32_e32 v1, 0x2000, v0
	v_ashrrev_i32_e32 v2, 31, v1
	v_lshrrev_b32_e32 v2, 22, v2
	v_add_u32_e32 v2, v1, v2
	s_load_dwordx2 s[8:9], s[6:7], 0xa8
	v_ashrrev_i32_e32 v8, 10, v2
	v_mul_i32_i24_e32 v2, 0x400, v8
	v_sub_u32_e32 v1, v1, v2
	v_lshrrev_b32_e32 v2, 4, v1
	v_bitop3_b32 v1, v2, v1, 32 bitop3:0x6c
	s_waitcnt lgkmcnt(0)
	s_add_u32 s4, s8, 0xd400000
	v_ashrrev_i32_e32 v2, 31, v1
	s_addc_u32 s5, s9, 0
	v_readlane_b32 s1, v240, 37
	v_lshrrev_b32_e32 v2, 26, v2
	s_add_u32 s1, s8, s1
	v_add_u32_e32 v2, v1, v2
	v_lshlrev_b32_e32 v3, 3, v8
	s_addc_u32 s6, s9, 0
	v_ashrrev_i32_e32 v9, 6, v2
	v_and_b32_e32 v3, -16, v3
	s_add_u32 s26, s1, 0x2a00000
	v_add_u32_e32 v3, v9, v3
	s_addc_u32 s27, s6, 0
	v_and_b32_e32 v4, 3, v9
	s_mov_b32 s6, 0xfffe0
	v_lshrrev_b32_e32 v5, 2, v3
	v_lshlrev_b32_e32 v6, 1, v3
	v_and_b32_e32 v2, 0xc0, v2
	v_and_or_b32 v4, v3, s6, v4
	v_and_b32_e32 v5, 4, v5
	v_and_b32_e32 v6, 24, v6
	v_sub_u32_e32 v1, v1, v2
	v_or3_b32 v4, v4, v5, v6
	v_lshlrev_b32_e32 v5, 5, v8
	v_ashrrev_i16_sdwa v1, v180, sext(v1) dst_sel:DWORD dst_unused:UNUSED_PAD src0_sel:DWORD src1_sel:BYTE_0
	v_and_b32_e32 v5, 32, v5
	v_bfe_i32 v10, v1, 0, 16
	v_add_lshl_u32 v1, v5, v10, 1
	v_lshl_add_u32 v128, v4, 12, v1
	v_lshl_add_u32 v130, v3, 12, v1
	v_bfe_i32 v1, v14, 27, 1
	v_lshrrev_b32_e32 v1, 22, v1
	v_add_u32_e32 v1, v0, v1
	v_and_b32_e32 v1, 0xfffffc00, v1
	v_sub_u32_e32 v0, v0, v1
	v_lshrrev_b32_e32 v1, 4, v0
	v_ashrrev_i32_e32 v2, 31, v14
	v_bitop3_b32 v0, v1, v0, 32 bitop3:0x6c
	v_lshrrev_b32_e32 v2, 26, v2
	v_ashrrev_i32_e32 v1, 31, v0
	v_add_u32_e32 v2, v14, v2
	v_lshrrev_b32_e32 v1, 26, v1
	v_ashrrev_i32_e32 v12, 6, v2
	v_add_u32_e32 v1, v0, v1
	v_lshlrev_b32_e32 v2, 3, v12
	v_ashrrev_i32_e32 v11, 6, v1
	v_and_b32_e32 v2, -16, v2
	v_add_u32_e32 v2, v11, v2
	v_and_b32_e32 v3, 3, v11
	v_lshrrev_b32_e32 v4, 2, v2
	v_lshlrev_b32_e32 v5, 1, v2
	v_and_b32_e32 v1, 0xc0, v1
	s_ashr_i32 s1, s0, 6
	v_and_or_b32 v3, v2, s6, v3
	v_and_b32_e32 v4, 4, v4
	v_and_b32_e32 v5, 24, v5
	v_sub_u32_e32 v0, v0, v1
	s_ashr_i32 s14, s0, 8
	s_lshl_b32 s35, s1, 10
	v_or3_b32 v3, v3, v4, v5
	v_lshlrev_b32_e32 v4, 5, v12
	v_ashrrev_i16_sdwa v0, v180, sext(v0) dst_sel:DWORD dst_unused:UNUSED_PAD src0_sel:DWORD src1_sel:BYTE_0
	v_readlane_b32 s6, v240, 4
	v_and_b32_e32 v4, 32, v4
	v_bfe_i32 v13, v0, 0, 16
	v_readlane_b32 s7, v240, 5
	s_add_u32 s28, s26, s6
	v_add_lshl_u32 v0, v4, v13, 1
	s_addc_u32 s29, s27, s7
	s_add_i32 s46, s35, 0
	v_lshl_add_u32 v144, v3, 12, v0
	s_add_i32 m0, s46, 0x10000
	v_lshl_add_u32 v132, v2, 12, v0
	global_load_lds_dwordx4 v144, s[28:29]
	s_add_i32 m0, s46, 0x12000
	s_add_u32 s6, s28, 0x80000
	global_load_lds_dwordx4 v128, s[28:29]
	s_addc_u32 s7, s29, 0
	s_add_i32 m0, s46, 0x14000
	v_mov_b32_e32 v129, v145
	global_load_lds_dwordx4 v144, s[6:7]
	s_add_i32 m0, s46, 0x16000
	v_mov_b32_e32 v133, v145
	global_load_lds_dwordx4 v128, s[6:7]
	v_readlane_b32 s6, v240, 24
	v_readlane_b32 s7, v240, 25
	s_add_u32 s24, s4, s6
	s_addc_u32 s25, s5, s7
	s_add_i32 s47, s46, 0x2000
	s_mov_b32 m0, s46
	s_add_u32 s6, s24, 0x80000
	global_load_lds_dwordx4 v132, s[24:25]
	s_mov_b32 m0, s47
	s_addc_u32 s7, s25, 0
	s_add_i32 s48, s46, 0x4000
	global_load_lds_dwordx4 v130, s[24:25]
	s_mov_b32 m0, s48
	s_add_i32 s49, s46, 0x6000
	global_load_lds_dwordx4 v132, s[6:7]
	s_mov_b32 m0, s49
	v_mov_b32_e32 v131, v145
	global_load_lds_dwordx4 v130, s[6:7]
	s_cmp_eq_u32 s14, 1
	v_lshl_add_u64 v[6:7], s[28:29], 0, v[144:145]
	v_lshl_add_u64 v[4:5], s[28:29], 0, v[128:129]
	v_lshl_add_u64 v[0:1], s[24:25], 0, v[132:133]
	s_cselect_b64 s[6:7], -1, 0
	s_cmp_lg_u32 s14, 1
	v_lshl_add_u64 v[2:3], s[24:25], 0, v[130:131]
	s_cbranch_scc1 .LBB0_985
	s_barrier
	s_setprio 1

.LBB0_991:
	s_add_u32 s28, s24, 0xfff80080
	s_addc_u32 s29, s25, -1
	s_add_i32 s60, 0, 0x10000
	s_cmp_eq_u32 s58, 28
	s_cselect_b32 s31, s19, s29
	s_cselect_b32 s30, s39, s28
	v_add_u32_e32 v138, s60, v141
	s_cselect_b32 s29, s17, s57
	s_cselect_b32 s28, s55, s56
	s_add_i32 s62, 0, 0x14000
	ds_read_b128 v[152:155], v138
	ds_read_b128 v[156:159], v138 offset:1024
	ds_read_b128 v[160:163], v138 offset:2048
	ds_read_b128 v[164:167], v138 offset:3072
	v_add_u32_e32 v138, s62, v141
	ds_read_b128 v[168:171], v138
	ds_read_b128 v[186:189], v138 offset:1024
	ds_read_b128 v[190:193], v138 offset:2048
	ds_read_b128 v[194:197], v138 offset:3072
	v_lshl_add_u64 v[138:139], s[24:25], 0, v[134:135]
	s_add_i32 m0, s46, 0xc000
	ds_read_b128 v[198:201], v143
	ds_read_b128 v[202:205], v143 offset:1024
	ds_read_b128 v[206:209], v143 offset:2048
	ds_read_b128 v[210:213], v143 offset:3072
	ds_read_b128 v[214:217], v143 offset:4096
	ds_read_b128 v[218:221], v143 offset:5120
	ds_read_b128 v[222:225], v143 offset:6144
	ds_read_b128 v[226:229], v143 offset:7168
	global_load_lds_dwordx4 v[138:139], off
	v_lshl_add_u64 v[138:139], s[24:25], 0, v[136:137]
	s_add_i32 m0, s46, 0xe000
	s_nop 0
	global_load_lds_dwordx4 v[138:139], off
	s_waitcnt vmcnt(8)
	s_waitcnt lgkmcnt(0)
	s_barrier
	s_waitcnt lgkmcnt(0)
	v_mfma_f32_16x16x32_bf16 v[124:127], v[152:155], v[198:201], v[124:127]
	v_mfma_f32_16x16x32_bf16 v[120:123], v[160:163], v[198:201], v[120:123]
	v_mfma_f32_16x16x32_bf16 v[108:111], v[152:155], v[206:209], v[108:111]
	v_mfma_f32_16x16x32_bf16 v[104:107], v[160:163], v[206:209], v[104:107]
	v_mfma_f32_16x16x32_bf16 v[92:95], v[152:155], v[214:217], v[92:95]
	v_mfma_f32_16x16x32_bf16 v[88:91], v[160:163], v[214:217], v[88:91]
	v_mfma_f32_16x16x32_bf16 v[76:79], v[152:155], v[222:225], v[76:79]
	v_mfma_f32_16x16x32_bf16 v[72:75], v[160:163], v[222:225], v[72:75]
	v_mfma_f32_16x16x32_bf16 v[124:127], v[156:159], v[202:205], v[124:127]
	v_mfma_f32_16x16x32_bf16 v[120:123], v[164:167], v[202:205], v[120:123]
	v_mfma_f32_16x16x32_bf16 v[108:111], v[156:159], v[210:213], v[108:111]
	v_mfma_f32_16x16x32_bf16 v[104:107], v[164:167], v[210:213], v[104:107]
	v_mfma_f32_16x16x32_bf16 v[92:95], v[156:159], v[218:221], v[92:95]
	v_mfma_f32_16x16x32_bf16 v[88:91], v[164:167], v[218:221], v[88:91]
	v_mfma_f32_16x16x32_bf16 v[76:79], v[156:159], v[226:229], v[76:79]
	v_mfma_f32_16x16x32_bf16 v[72:75], v[164:167], v[226:229], v[72:75]
	v_mfma_f32_16x16x32_bf16 v[116:119], v[168:171], v[198:201], v[116:119]
	v_mfma_f32_16x16x32_bf16 v[112:115], v[190:193], v[198:201], v[112:115]
	v_mfma_f32_16x16x32_bf16 v[100:103], v[168:171], v[206:209], v[100:103]
	v_mfma_f32_16x16x32_bf16 v[96:99], v[190:193], v[206:209], v[96:99]
	v_mfma_f32_16x16x32_bf16 v[84:87], v[168:171], v[214:217], v[84:87]
	v_mfma_f32_16x16x32_bf16 v[80:83], v[190:193], v[214:217], v[80:83]
	v_mfma_f32_16x16x32_bf16 v[68:71], v[168:171], v[222:225], v[68:71]
	v_mfma_f32_16x16x32_bf16 v[64:67], v[190:193], v[222:225], v[64:67]
	v_mfma_f32_16x16x32_bf16 v[116:119], v[186:189], v[202:205], v[116:119]
	v_mfma_f32_16x16x32_bf16 v[112:115], v[194:197], v[202:205], v[112:115]
	v_mfma_f32_16x16x32_bf16 v[100:103], v[186:189], v[210:213], v[100:103]
	v_mfma_f32_16x16x32_bf16 v[96:99], v[194:197], v[210:213], v[96:99]
	v_mfma_f32_16x16x32_bf16 v[84:87], v[186:189], v[218:221], v[84:87]
	v_mfma_f32_16x16x32_bf16 v[80:83], v[194:197], v[218:221], v[80:83]
	v_mfma_f32_16x16x32_bf16 v[68:71], v[186:189], v[226:229], v[68:71]
	v_mfma_f32_16x16x32_bf16 v[64:67], v[194:197], v[226:229], v[64:67]
	s_barrier
	s_add_i32 s60, s60, s35
	v_lshl_add_u64 v[138:139], s[28:29], 0, v[144:145]
	s_mov_b32 m0, s60
	ds_read_b128 v[198:201], v143 offset:16384
	ds_read_b128 v[202:205], v143 offset:17408
	ds_read_b128 v[206:209], v143 offset:18432
	ds_read_b128 v[210:213], v143 offset:19456
	ds_read_b128 v[214:217], v143 offset:20480
	ds_read_b128 v[218:221], v143 offset:21504
	ds_read_b128 v[222:225], v143 offset:22528
	ds_read_b128 v[226:229], v143 offset:23552
	global_load_lds_dwordx4 v[138:139], off
	s_add_i32 m0, s60, 0x2000
	s_add_u32 s60, s28, 0x80000
	v_lshl_add_u64 v[230:231], s[28:29], 0, v[128:129]
	s_addc_u32 s61, s29, 0
	s_add_i32 s62, s62, s35
	global_load_lds_dwordx4 v[230:231], off
	v_lshl_add_u64 v[232:233], s[60:61], 0, v[144:145]
	s_mov_b32 m0, s62
	v_lshl_add_u64 v[234:235], s[30:31], 0, v[130:131]
	global_load_lds_dwordx4 v[232:233], off
	v_lshl_add_u64 v[232:233], s[60:61], 0, v[128:129]
	s_add_i32 m0, s62, 0x2000
	s_nop 0
	global_load_lds_dwordx4 v[232:233], off
	v_lshl_add_u64 v[232:233], s[30:31], 0, v[132:133]
	s_mov_b32 m0, s46
	s_nop 0
	global_load_lds_dwordx4 v[232:233], off
	s_mov_b32 m0, s47
	s_nop 0
	global_load_lds_dwordx4 v[234:235], off
	s_waitcnt vmcnt(8)
	s_waitcnt lgkmcnt(0)
	s_barrier
	s_waitcnt lgkmcnt(0)
	v_mfma_f32_16x16x32_bf16 v[60:63], v[152:155], v[198:201], v[60:63]
	v_mfma_f32_16x16x32_bf16 v[56:59], v[160:163], v[198:201], v[56:59]
	v_mfma_f32_16x16x32_bf16 v[44:47], v[152:155], v[206:209], v[44:47]
	v_mfma_f32_16x16x32_bf16 v[40:43], v[160:163], v[206:209], v[40:43]
	v_mfma_f32_16x16x32_bf16 v[28:31], v[152:155], v[214:217], v[28:31]
	v_mfma_f32_16x16x32_bf16 v[24:27], v[160:163], v[214:217], v[24:27]
	v_mfma_f32_16x16x32_bf16 v[12:15], v[152:155], v[222:225], v[12:15]
	v_mfma_f32_16x16x32_bf16 v[8:11], v[160:163], v[222:225], v[8:11]
	v_mfma_f32_16x16x32_bf16 v[60:63], v[156:159], v[202:205], v[60:63]
	v_mfma_f32_16x16x32_bf16 v[56:59], v[164:167], v[202:205], v[56:59]
	v_mfma_f32_16x16x32_bf16 v[44:47], v[156:159], v[210:213], v[44:47]
	v_mfma_f32_16x16x32_bf16 v[40:43], v[164:167], v[210:213], v[40:43]
	v_mfma_f32_16x16x32_bf16 v[28:31], v[156:159], v[218:221], v[28:31]
	v_mfma_f32_16x16x32_bf16 v[24:27], v[164:167], v[218:221], v[24:27]
	v_mfma_f32_16x16x32_bf16 v[12:15], v[156:159], v[226:229], v[12:15]
	v_mfma_f32_16x16x32_bf16 v[8:11], v[164:167], v[226:229], v[8:11]
	v_mfma_f32_16x16x32_bf16 v[52:55], v[168:171], v[198:201], v[52:55]
	v_mfma_f32_16x16x32_bf16 v[48:51], v[190:193], v[198:201], v[48:51]
	v_mfma_f32_16x16x32_bf16 v[36:39], v[168:171], v[206:209], v[36:39]
	v_mfma_f32_16x16x32_bf16 v[32:35], v[190:193], v[206:209], v[32:35]
	v_mfma_f32_16x16x32_bf16 v[20:23], v[168:171], v[214:217], v[20:23]
	v_mfma_f32_16x16x32_bf16 v[16:19], v[190:193], v[214:217], v[16:19]
	v_mfma_f32_16x16x32_bf16 v[4:7], v[168:171], v[222:225], v[4:7]
	v_mfma_f32_16x16x32_bf16 v[0:3], v[190:193], v[222:225], v[0:3]
	v_mfma_f32_16x16x32_bf16 v[52:55], v[186:189], v[202:205], v[52:55]
	v_mfma_f32_16x16x32_bf16 v[48:51], v[194:197], v[202:205], v[48:51]
	v_mfma_f32_16x16x32_bf16 v[36:39], v[186:189], v[210:213], v[36:39]
	v_mfma_f32_16x16x32_bf16 v[32:35], v[194:197], v[210:213], v[32:35]
	v_mfma_f32_16x16x32_bf16 v[20:23], v[186:189], v[218:221], v[20:23]
	v_mfma_f32_16x16x32_bf16 v[16:19], v[194:197], v[218:221], v[16:19]
	v_mfma_f32_16x16x32_bf16 v[4:7], v[186:189], v[226:229], v[4:7]
	v_mfma_f32_16x16x32_bf16 v[0:3], v[194:197], v[226:229], v[0:3]
	s_barrier
	s_add_i32 s60, 0, 0x18000
	s_add_i32 s61, 0, 0x1c000
	v_add_u32_e32 v164, s60, v141
	v_add_u32_e32 v185, s61, v141
	ds_read_b128 v[152:155], v164
	ds_read_b128 v[156:159], v164 offset:1024
	ds_read_b128 v[160:163], v164 offset:2048
	ds_read_b128 v[164:167], v164 offset:3072
	ds_read_b128 v[168:171], v185
	ds_read_b128 v[186:189], v185 offset:1024
	ds_read_b128 v[190:193], v185 offset:2048
	ds_read_b128 v[194:197], v185 offset:3072
	s_add_u32 s30, s30, 0x80000
	s_addc_u32 s31, s31, 0
	s_mov_b32 m0, s48
	v_lshl_add_u64 v[236:237], s[30:31], 0, v[132:133]
	ds_read_b128 v[198:201], v143 offset:32768
	ds_read_b128 v[202:205], v143 offset:33792
	ds_read_b128 v[206:209], v143 offset:34816
	ds_read_b128 v[210:213], v143 offset:35840
	ds_read_b128 v[214:217], v143 offset:36864
	ds_read_b128 v[218:221], v143 offset:37888
	ds_read_b128 v[222:225], v143 offset:38912
	ds_read_b128 v[226:229], v143 offset:39936
	global_load_lds_dwordx4 v[236:237], off
	v_lshl_add_u64 v[236:237], s[30:31], 0, v[130:131]
	s_mov_b32 m0, s49
	s_nop 0
	global_load_lds_dwordx4 v[236:237], off
	s_waitcnt vmcnt(8)
	s_waitcnt lgkmcnt(0)
	s_barrier
	s_waitcnt lgkmcnt(0)
	v_mfma_f32_16x16x32_bf16 v[124:127], v[152:155], v[198:201], v[124:127]
	v_mfma_f32_16x16x32_bf16 v[120:123], v[160:163], v[198:201], v[120:123]
	v_mfma_f32_16x16x32_bf16 v[108:111], v[152:155], v[206:209], v[108:111]
	v_mfma_f32_16x16x32_bf16 v[104:107], v[160:163], v[206:209], v[104:107]
	v_mfma_f32_16x16x32_bf16 v[92:95], v[152:155], v[214:217], v[92:95]
	v_mfma_f32_16x16x32_bf16 v[88:91], v[160:163], v[214:217], v[88:91]
	v_mfma_f32_16x16x32_bf16 v[76:79], v[152:155], v[222:225], v[76:79]
	v_mfma_f32_16x16x32_bf16 v[72:75], v[160:163], v[222:225], v[72:75]
	v_mfma_f32_16x16x32_bf16 v[124:127], v[156:159], v[202:205], v[124:127]
	v_mfma_f32_16x16x32_bf16 v[120:123], v[164:167], v[202:205], v[120:123]
	v_mfma_f32_16x16x32_bf16 v[108:111], v[156:159], v[210:213], v[108:111]
	v_mfma_f32_16x16x32_bf16 v[104:107], v[164:167], v[210:213], v[104:107]
	v_mfma_f32_16x16x32_bf16 v[92:95], v[156:159], v[218:221], v[92:95]
	v_mfma_f32_16x16x32_bf16 v[88:91], v[164:167], v[218:221], v[88:91]
	v_mfma_f32_16x16x32_bf16 v[76:79], v[156:159], v[226:229], v[76:79]
	v_mfma_f32_16x16x32_bf16 v[72:75], v[164:167], v[226:229], v[72:75]
	v_mfma_f32_16x16x32_bf16 v[116:119], v[168:171], v[198:201], v[116:119]
	v_mfma_f32_16x16x32_bf16 v[112:115], v[190:193], v[198:201], v[112:115]
	v_mfma_f32_16x16x32_bf16 v[100:103], v[168:171], v[206:209], v[100:103]
	v_mfma_f32_16x16x32_bf16 v[96:99], v[190:193], v[206:209], v[96:99]
	v_mfma_f32_16x16x32_bf16 v[84:87], v[168:171], v[214:217], v[84:87]
	v_mfma_f32_16x16x32_bf16 v[80:83], v[190:193], v[214:217], v[80:83]
	v_mfma_f32_16x16x32_bf16 v[68:71], v[168:171], v[222:225], v[68:71]
	v_mfma_f32_16x16x32_bf16 v[64:67], v[190:193], v[222:225], v[64:67]
	v_mfma_f32_16x16x32_bf16 v[116:119], v[186:189], v[202:205], v[116:119]
	v_mfma_f32_16x16x32_bf16 v[112:115], v[194:197], v[202:205], v[112:115]
	v_mfma_f32_16x16x32_bf16 v[100:103], v[186:189], v[210:213], v[100:103]
	v_mfma_f32_16x16x32_bf16 v[96:99], v[194:197], v[210:213], v[96:99]
	v_mfma_f32_16x16x32_bf16 v[84:87], v[186:189], v[218:221], v[84:87]
	v_mfma_f32_16x16x32_bf16 v[80:83], v[194:197], v[218:221], v[80:83]
	v_mfma_f32_16x16x32_bf16 v[68:71], v[186:189], v[226:229], v[68:71]
	v_mfma_f32_16x16x32_bf16 v[64:67], v[194:197], v[226:229], v[64:67]
	s_barrier
	s_add_i32 s30, s60, s35
	v_lshl_add_u64 v[138:139], v[138:139], 0, s[68:69]
	s_mov_b32 m0, s30
	ds_read_b128 v[198:201], v143 offset:49152
	ds_read_b128 v[202:205], v143 offset:50176
	ds_read_b128 v[206:209], v143 offset:51200
	ds_read_b128 v[210:213], v143 offset:52224
	ds_read_b128 v[214:217], v143 offset:53248
	ds_read_b128 v[218:221], v143 offset:54272
	ds_read_b128 v[222:225], v143 offset:55296
	ds_read_b128 v[226:229], v143 offset:56320
	global_load_lds_dwordx4 v[138:139], off
	s_add_i32 m0, s30, 0x2000
	s_add_u32 s28, s28, 0x80080
	v_lshl_add_u64 v[138:139], v[230:231], 0, s[68:69]
	s_addc_u32 s29, s29, 0
	s_add_i32 s30, s61, s35
	global_load_lds_dwordx4 v[138:139], off
	v_lshl_add_u64 v[138:139], s[28:29], 0, v[144:145]
	s_mov_b32 m0, s30
	s_nop 0
	global_load_lds_dwordx4 v[138:139], off
	v_lshl_add_u64 v[138:139], s[28:29], 0, v[128:129]
	s_add_i32 m0, s30, 0x2000
	s_nop 0
	global_load_lds_dwordx4 v[138:139], off
	v_lshl_add_u64 v[138:139], v[232:233], 0, s[68:69]
	s_mov_b32 m0, s50
	s_nop 0
	global_load_lds_dwordx4 v[138:139], off
	v_lshl_add_u64 v[138:139], v[234:235], 0, s[68:69]
	s_mov_b32 m0, s51
	s_nop 0
	global_load_lds_dwordx4 v[138:139], off
	s_waitcnt vmcnt(8)
	s_waitcnt lgkmcnt(0)
	s_barrier
	s_waitcnt lgkmcnt(0)
	v_mfma_f32_16x16x32_bf16 v[60:63], v[152:155], v[198:201], v[60:63]
	v_mfma_f32_16x16x32_bf16 v[56:59], v[160:163], v[198:201], v[56:59]
	v_mfma_f32_16x16x32_bf16 v[44:47], v[152:155], v[206:209], v[44:47]
	v_mfma_f32_16x16x32_bf16 v[40:43], v[160:163], v[206:209], v[40:43]
	v_mfma_f32_16x16x32_bf16 v[28:31], v[152:155], v[214:217], v[28:31]
	v_mfma_f32_16x16x32_bf16 v[24:27], v[160:163], v[214:217], v[24:27]
	v_mfma_f32_16x16x32_bf16 v[12:15], v[152:155], v[222:225], v[12:15]
	v_mfma_f32_16x16x32_bf16 v[8:11], v[160:163], v[222:225], v[8:11]
	v_mfma_f32_16x16x32_bf16 v[60:63], v[156:159], v[202:205], v[60:63]
	v_mfma_f32_16x16x32_bf16 v[56:59], v[164:167], v[202:205], v[56:59]
	v_mfma_f32_16x16x32_bf16 v[44:47], v[156:159], v[210:213], v[44:47]
	v_mfma_f32_16x16x32_bf16 v[40:43], v[164:167], v[210:213], v[40:43]
	v_mfma_f32_16x16x32_bf16 v[28:31], v[156:159], v[218:221], v[28:31]
	v_mfma_f32_16x16x32_bf16 v[24:27], v[164:167], v[218:221], v[24:27]
	v_mfma_f32_16x16x32_bf16 v[12:15], v[156:159], v[226:229], v[12:15]
	v_mfma_f32_16x16x32_bf16 v[8:11], v[164:167], v[226:229], v[8:11]
	v_mfma_f32_16x16x32_bf16 v[52:55], v[168:171], v[198:201], v[52:55]
	v_mfma_f32_16x16x32_bf16 v[48:51], v[190:193], v[198:201], v[48:51]
	v_mfma_f32_16x16x32_bf16 v[36:39], v[168:171], v[206:209], v[36:39]
	v_mfma_f32_16x16x32_bf16 v[32:35], v[190:193], v[206:209], v[32:35]
	v_mfma_f32_16x16x32_bf16 v[20:23], v[168:171], v[214:217], v[20:23]
	v_mfma_f32_16x16x32_bf16 v[16:19], v[190:193], v[214:217], v[16:19]
	v_mfma_f32_16x16x32_bf16 v[4:7], v[168:171], v[222:225], v[4:7]
	v_mfma_f32_16x16x32_bf16 v[0:3], v[190:193], v[222:225], v[0:3]
	v_mfma_f32_16x16x32_bf16 v[52:55], v[186:189], v[202:205], v[52:55]
	v_mfma_f32_16x16x32_bf16 v[48:51], v[194:197], v[202:205], v[48:51]
	v_mfma_f32_16x16x32_bf16 v[36:39], v[186:189], v[210:213], v[36:39]
	v_mfma_f32_16x16x32_bf16 v[32:35], v[194:197], v[210:213], v[32:35]
	v_mfma_f32_16x16x32_bf16 v[20:23], v[186:189], v[218:221], v[20:23]
	v_mfma_f32_16x16x32_bf16 v[16:19], v[194:197], v[218:221], v[16:19]
	v_mfma_f32_16x16x32_bf16 v[4:7], v[186:189], v[226:229], v[4:7]
	v_mfma_f32_16x16x32_bf16 v[0:3], v[194:197], v[226:229], v[0:3]
	s_barrier
	s_add_i32 s58, s58, 2
	s_add_u32 s24, s24, 0x100
	s_addc_u32 s25, s25, 0
	s_add_u32 s56, s56, 0x100
	s_addc_u32 s57, s57, 0
	s_cmp_gt_u32 s58, 29
	s_cbranch_scc0 .LBB0_991
	s_and_b64 vcc, exec, s[14:15]
	s_cbranch_vccz .LBB0_994
	s_barrier

.LBB0_998:
	s_setprio 0
	s_mov_b64 s[8:9], s[76:77]
	s_getreg_b32 s0, hwreg(HW_REG_XCC_ID, 0, 4)
	s_waitcnt vmcnt(0)
	s_waitcnt vmcnt(0)
	s_barrier
	s_mov_b64 s[6:7], exec
	v_readlane_b32 s4, v241, 2
	v_readlane_b32 s5, v241, 3
	s_and_b64 s[4:5], s[6:7], s[4:5]
	s_mov_b64 exec, s[4:5]
	s_cbranch_execz .LBB0_1050
	v_readlane_b32 s1, v240, 13
	s_load_dwordx2 s[8:9], s[8:9], 0xa8
	s_waitcnt vmcnt(0) expcnt(0) lgkmcnt(0)
	v_mov_b32_e32 v0, s1
	ds_read_b32 v2, v0
	v_readlane_b32 s1, v240, 14
	s_and_b32 s0, s0, 15
	s_waitcnt lgkmcnt(0)
	v_cmp_ne_u32_e32 vcc, 0, v2
	v_mov_b32_e32 v0, s1
	ds_read_b32 v0, v0
	s_cbranch_vccnz .LBB0_1014
	s_add_u32 s12, s8, 0x1000
	s_addc_u32 s13, s9, 0
	s_add_u32 s14, s8, 0x1100
	s_addc_u32 s15, s9, 0
	s_add_u32 s16, s8, 0x1200
	s_addc_u32 s17, s9, 0
	s_add_u32 s18, s8, 0x1300
	s_addc_u32 s19, s9, 0
	s_mov_b32 s1, 1
	s_branch .LBB0_1002

.LBB0_1050:
	s_or_b64 exec, exec, s[6:7]
	s_mov_b64 s[6:7], s[76:77]
	v_mov_b32_e32 v14, v172
	s_waitcnt lgkmcnt(0)
	s_barrier
	s_and_b64 vcc, exec, s[10:11]
	v_readfirstlane_b32 s0, v14
	s_cbranch_vccnz .LBB0_66
	v_lshlrev_b32_e32 v0, 4, v14
	s_load_dwordx2 s[14:15], s[6:7], 0xa8
	v_add_u32_e32 v1, 0x2000, v0
	v_ashrrev_i32_e32 v2, 31, v1
	v_lshrrev_b32_e32 v2, 22, v2
	v_add_u32_e32 v2, v1, v2
	v_ashrrev_i32_e32 v8, 10, v2
	s_waitcnt lgkmcnt(0)
	s_add_u32 s16, s14, 0x10400000
	v_mul_i32_i24_e32 v2, 0x400, v8
	s_addc_u32 s17, s15, 0
	v_readlane_b32 s1, v240, 37
	v_sub_u32_e32 v1, v1, v2
	s_add_u32 s21, s14, s1
	v_lshrrev_b32_e32 v2, 4, v1
	s_addc_u32 s22, s15, 0
	v_bitop3_b32 v1, v2, v1, 32 bitop3:0x6c
	s_add_u32 s19, s21, 0x4a00000
	v_ashrrev_i32_e32 v2, 31, v1
	s_addc_u32 s20, s22, 0
	v_readlane_b32 s1, v240, 0
	v_lshrrev_b32_e32 v2, 26, v2
	s_add_u32 s8, s19, s1
	v_add_u32_e32 v2, v1, v2
	v_lshlrev_b32_e32 v3, 3, v8
	s_addc_u32 s9, s20, 0
	v_readlane_b32 s4, v241, 61
	v_ashrrev_i32_e32 v9, 6, v2
	v_and_b32_e32 v3, -16, v3
	v_readlane_b32 s5, v241, 62
	s_add_u32 s6, s16, s4
	v_add_u32_e32 v3, v9, v3
	s_addc_u32 s7, s17, s5
	v_and_b32_e32 v4, 3, v9
	s_mov_b32 s5, 0x3ffe0
	v_lshrrev_b32_e32 v5, 2, v3
	v_lshlrev_b32_e32 v6, 1, v3
	v_and_b32_e32 v2, 0xc0, v2
	v_and_or_b32 v4, v3, s5, v4
	v_and_b32_e32 v5, 4, v5
	v_and_b32_e32 v6, 24, v6
	v_sub_u32_e32 v1, v1, v2
	v_or3_b32 v4, v4, v5, v6
	v_lshlrev_b32_e32 v5, 5, v8
	v_ashrrev_i16_sdwa v1, v180, sext(v1) dst_sel:DWORD dst_unused:UNUSED_PAD src0_sel:DWORD src1_sel:BYTE_0
	v_and_b32_e32 v5, 32, v5
	v_bfe_i32 v10, v1, 0, 16
	v_add_lshl_u32 v1, v5, v10, 1
	v_lshl_add_u32 v136, v4, 14, v1
	v_lshl_add_u32 v138, v3, 14, v1
	v_bfe_i32 v1, v14, 27, 1
	v_lshrrev_b32_e32 v1, 22, v1
	v_add_u32_e32 v1, v0, v1
	v_and_b32_e32 v1, 0xfffffc00, v1
	v_sub_u32_e32 v0, v0, v1
	v_lshrrev_b32_e32 v1, 4, v0
	v_ashrrev_i32_e32 v2, 31, v14
	v_bitop3_b32 v0, v1, v0, 32 bitop3:0x6c
	v_lshrrev_b32_e32 v2, 26, v2
	v_ashrrev_i32_e32 v1, 31, v0
	v_add_u32_e32 v2, v14, v2
	v_lshrrev_b32_e32 v1, 26, v1
	v_ashrrev_i32_e32 v12, 6, v2
	v_add_u32_e32 v1, v0, v1
	v_lshlrev_b32_e32 v2, 3, v12
	v_ashrrev_i32_e32 v11, 6, v1
	v_and_b32_e32 v2, -16, v2
	s_ashr_i32 s1, s0, 6
	v_add_u32_e32 v2, v11, v2
	s_ashr_i32 s18, s0, 8
	s_lshl_b32 s4, s1, 10
	v_and_b32_e32 v3, 3, v11
	v_lshrrev_b32_e32 v4, 2, v2
	v_lshlrev_b32_e32 v5, 1, v2
	v_and_b32_e32 v1, 0xc0, v1
	s_add_u32 s10, s6, 0x200000
	v_and_or_b32 v3, v2, s5, v3
	v_and_b32_e32 v4, 4, v4
	v_and_b32_e32 v5, 24, v5
	v_sub_u32_e32 v0, v0, v1
	s_addc_u32 s11, s7, 0
	v_or3_b32 v3, v3, v4, v5
	v_lshlrev_b32_e32 v4, 5, v12
	v_ashrrev_i16_sdwa v0, v180, sext(v0) dst_sel:DWORD dst_unused:UNUSED_PAD src0_sel:DWORD src1_sel:BYTE_0
	s_add_u32 s12, s8, 0x200000
	v_and_b32_e32 v4, 32, v4
	v_bfe_i32 v13, v0, 0, 16
	s_addc_u32 s13, s9, 0
	v_add_lshl_u32 v0, v4, v13, 1
	s_add_i32 s5, s4, 0
	v_lshl_add_u32 v140, v3, 14, v0
	s_add_i32 m0, s5, 0x10000
	v_lshl_add_u32 v142, v2, 14, v0
	global_load_lds_dwordx4 v140, s[8:9]
	s_add_i32 m0, s5, 0x12000
	s_add_i32 s26, s5, 0x2000
	global_load_lds_dwordx4 v136, s[8:9]
	s_add_i32 m0, s5, 0x14000
	s_add_i32 s27, s5, 0x4000
	global_load_lds_dwordx4 v140, s[12:13]
	s_add_i32 m0, s5, 0x16000
	s_add_i32 s28, s5, 0x6000
	global_load_lds_dwordx4 v136, s[12:13]
	s_mov_b32 m0, s5
	v_mov_b32_e32 v141, v145
	global_load_lds_dwordx4 v142, s[6:7]
	s_mov_b32 m0, s26
	v_mov_b32_e32 v137, v145
	global_load_lds_dwordx4 v138, s[6:7]
	s_mov_b32 m0, s27
	v_mov_b32_e32 v143, v145
	global_load_lds_dwordx4 v142, s[10:11]
	s_mov_b32 m0, s28
	v_mov_b32_e32 v139, v145
	global_load_lds_dwordx4 v138, s[10:11]
	s_cmp_eq_u32 s18, 1
	v_lshl_add_u64 v[6:7], s[8:9], 0, v[140:141]
	v_lshl_add_u64 v[4:5], s[8:9], 0, v[136:137]
	v_lshl_add_u64 v[0:1], s[6:7], 0, v[142:143]
	s_cselect_b64 s[10:11], -1, 0
	s_cmp_lg_u32 s18, 1
	v_lshl_add_u64 v[2:3], s[6:7], 0, v[138:139]
	s_cbranch_scc1 .LBB0_1053
	s_barrier
	s_setprio 1

.LBB0_1057:
	s_add_u32 s22, s20, 0xffe00080
	s_addc_u32 s23, s21, -1
	s_add_i32 s62, 0, 0x10000
	s_cmp_eq_u32 s39, s61
	s_cselect_b32 s25, s17, s23
	s_cselect_b32 s24, s55, s22
	v_add_u32_e32 v144, s62, v163
	s_cselect_b32 s23, s56, s60
	s_cselect_b32 s22, s57, s58
	s_add_i32 s67, 0, 0x14000
	ds_read_b128 v[104:107], v144
	ds_read_b128 v[108:111], v144 offset:1024
	ds_read_b128 v[156:159], v144 offset:2048
	ds_read_b128 v[166:169], v144 offset:3072
	v_add_u32_e32 v144, s67, v163
	ds_read_b128 v[186:189], v144
	ds_read_b128 v[190:193], v144 offset:1024
	ds_read_b128 v[194:197], v144 offset:2048
	ds_read_b128 v[198:201], v144 offset:3072
	v_lshl_add_u64 v[160:161], s[20:21], 0, v[152:153]
	s_add_i32 m0, s5, 0xc000
	ds_read_b128 v[202:205], v165
	ds_read_b128 v[206:209], v165 offset:1024
	ds_read_b128 v[210:213], v165 offset:2048
	ds_read_b128 v[214:217], v165 offset:3072
	ds_read_b128 v[218:221], v165 offset:4096
	ds_read_b128 v[222:225], v165 offset:5120
	ds_read_b128 v[226:229], v165 offset:6144
	ds_read_b128 v[230:233], v165 offset:7168
	global_load_lds_dwordx4 v[160:161], off
	v_lshl_add_u64 v[160:161], s[20:21], 0, v[154:155]
	s_add_i32 m0, s5, 0xe000
	s_nop 0
	global_load_lds_dwordx4 v[160:161], off
	s_waitcnt vmcnt(8)
	s_waitcnt lgkmcnt(0)
	s_barrier
	s_waitcnt lgkmcnt(0)
	v_mfma_f32_16x16x32_bf16 v[132:135], v[104:107], v[202:205], v[132:135]
	v_mfma_f32_16x16x32_bf16 v[128:131], v[156:159], v[202:205], v[128:131]
	v_mfma_f32_16x16x32_bf16 v[124:127], v[104:107], v[210:213], v[124:127]
	v_mfma_f32_16x16x32_bf16 v[120:123], v[156:159], v[210:213], v[120:123]
	v_mfma_f32_16x16x32_bf16 v[116:119], v[104:107], v[218:221], v[116:119]
	v_mfma_f32_16x16x32_bf16 v[112:115], v[156:159], v[218:221], v[112:115]
	v_mfma_f32_16x16x32_bf16 v[100:103], v[104:107], v[226:229], v[100:103]
	v_mfma_f32_16x16x32_bf16 v[96:99], v[156:159], v[226:229], v[96:99]
	v_mfma_f32_16x16x32_bf16 v[132:135], v[108:111], v[206:209], v[132:135]
	v_mfma_f32_16x16x32_bf16 v[128:131], v[166:169], v[206:209], v[128:131]
	v_mfma_f32_16x16x32_bf16 v[124:127], v[108:111], v[214:217], v[124:127]
	v_mfma_f32_16x16x32_bf16 v[120:123], v[166:169], v[214:217], v[120:123]
	v_mfma_f32_16x16x32_bf16 v[116:119], v[108:111], v[222:225], v[116:119]
	v_mfma_f32_16x16x32_bf16 v[112:115], v[166:169], v[222:225], v[112:115]
	v_mfma_f32_16x16x32_bf16 v[100:103], v[108:111], v[230:233], v[100:103]
	v_mfma_f32_16x16x32_bf16 v[96:99], v[166:169], v[230:233], v[96:99]
	v_mfma_f32_16x16x32_bf16 v[60:63], v[186:189], v[202:205], v[60:63]
	v_mfma_f32_16x16x32_bf16 v[56:59], v[194:197], v[202:205], v[56:59]
	v_mfma_f32_16x16x32_bf16 v[52:55], v[186:189], v[210:213], v[52:55]
	v_mfma_f32_16x16x32_bf16 v[48:51], v[194:197], v[210:213], v[48:51]
	v_mfma_f32_16x16x32_bf16 v[44:47], v[186:189], v[218:221], v[44:47]
	v_mfma_f32_16x16x32_bf16 v[40:43], v[194:197], v[218:221], v[40:43]
	v_mfma_f32_16x16x32_bf16 v[36:39], v[186:189], v[226:229], v[36:39]
	v_mfma_f32_16x16x32_bf16 v[32:35], v[194:197], v[226:229], v[32:35]
	v_mfma_f32_16x16x32_bf16 v[60:63], v[190:193], v[206:209], v[60:63]
	v_mfma_f32_16x16x32_bf16 v[56:59], v[198:201], v[206:209], v[56:59]
	v_mfma_f32_16x16x32_bf16 v[52:55], v[190:193], v[214:217], v[52:55]
	v_mfma_f32_16x16x32_bf16 v[48:51], v[198:201], v[214:217], v[48:51]
	v_mfma_f32_16x16x32_bf16 v[44:47], v[190:193], v[222:225], v[44:47]
	v_mfma_f32_16x16x32_bf16 v[40:43], v[198:201], v[222:225], v[40:43]
	v_mfma_f32_16x16x32_bf16 v[36:39], v[190:193], v[230:233], v[36:39]
	v_mfma_f32_16x16x32_bf16 v[32:35], v[198:201], v[230:233], v[32:35]
	s_barrier
	s_add_i32 s62, s62, s4
	v_lshl_add_u64 v[160:161], s[22:23], 0, v[140:141]
	s_mov_b32 m0, s62
	ds_read_b128 v[202:205], v165 offset:16384
	ds_read_b128 v[206:209], v165 offset:17408
	ds_read_b128 v[210:213], v165 offset:18432
	ds_read_b128 v[214:217], v165 offset:19456
	ds_read_b128 v[218:221], v165 offset:20480
	ds_read_b128 v[222:225], v165 offset:21504
	ds_read_b128 v[226:229], v165 offset:22528
	ds_read_b128 v[230:233], v165 offset:23552
	global_load_lds_dwordx4 v[160:161], off
	s_add_i32 m0, s62, 0x2000
	s_add_u32 s62, s22, 0x200000
	v_lshl_add_u64 v[170:171], s[22:23], 0, v[136:137]
	s_addc_u32 s63, s23, 0
	s_add_i32 s67, s67, s4
	global_load_lds_dwordx4 v[170:171], off
	v_lshl_add_u64 v[234:235], s[62:63], 0, v[140:141]
	s_mov_b32 m0, s67
	v_lshl_add_u64 v[236:237], s[24:25], 0, v[138:139]
	global_load_lds_dwordx4 v[234:235], off
	v_lshl_add_u64 v[234:235], s[62:63], 0, v[136:137]
	s_add_i32 m0, s67, 0x2000
	s_nop 0
	global_load_lds_dwordx4 v[234:235], off
	v_lshl_add_u64 v[234:235], s[24:25], 0, v[142:143]
	s_mov_b32 m0, s5
	s_nop 0
	global_load_lds_dwordx4 v[234:235], off
	s_mov_b32 m0, s26
	s_nop 0
	global_load_lds_dwordx4 v[236:237], off
	s_waitcnt vmcnt(8)
	s_waitcnt lgkmcnt(0)
	s_barrier
	s_waitcnt lgkmcnt(0)
	v_mfma_f32_16x16x32_bf16 v[92:95], v[104:107], v[202:205], v[92:95]
	v_mfma_f32_16x16x32_bf16 v[88:91], v[156:159], v[202:205], v[88:91]
	v_mfma_f32_16x16x32_bf16 v[84:87], v[104:107], v[210:213], v[84:87]
	v_mfma_f32_16x16x32_bf16 v[80:83], v[156:159], v[210:213], v[80:83]
	v_mfma_f32_16x16x32_bf16 v[76:79], v[104:107], v[218:221], v[76:79]
	v_mfma_f32_16x16x32_bf16 v[72:75], v[156:159], v[218:221], v[72:75]
	v_mfma_f32_16x16x32_bf16 v[68:71], v[104:107], v[226:229], v[68:71]
	v_mfma_f32_16x16x32_bf16 v[64:67], v[156:159], v[226:229], v[64:67]
	v_mfma_f32_16x16x32_bf16 v[92:95], v[108:111], v[206:209], v[92:95]
	v_mfma_f32_16x16x32_bf16 v[88:91], v[166:169], v[206:209], v[88:91]
	v_mfma_f32_16x16x32_bf16 v[84:87], v[108:111], v[214:217], v[84:87]
	v_mfma_f32_16x16x32_bf16 v[80:83], v[166:169], v[214:217], v[80:83]
	v_mfma_f32_16x16x32_bf16 v[76:79], v[108:111], v[222:225], v[76:79]
	v_mfma_f32_16x16x32_bf16 v[72:75], v[166:169], v[222:225], v[72:75]
	v_mfma_f32_16x16x32_bf16 v[68:71], v[108:111], v[230:233], v[68:71]
	v_mfma_f32_16x16x32_bf16 v[64:67], v[166:169], v[230:233], v[64:67]
	v_mfma_f32_16x16x32_bf16 v[28:31], v[186:189], v[202:205], v[28:31]
	v_mfma_f32_16x16x32_bf16 v[24:27], v[194:197], v[202:205], v[24:27]
	v_mfma_f32_16x16x32_bf16 v[20:23], v[186:189], v[210:213], v[20:23]
	v_mfma_f32_16x16x32_bf16 v[16:19], v[194:197], v[210:213], v[16:19]
	v_mfma_f32_16x16x32_bf16 v[12:15], v[186:189], v[218:221], v[12:15]
	v_mfma_f32_16x16x32_bf16 v[8:11], v[194:197], v[218:221], v[8:11]
	v_mfma_f32_16x16x32_bf16 v[4:7], v[186:189], v[226:229], v[4:7]
	v_mfma_f32_16x16x32_bf16 v[0:3], v[194:197], v[226:229], v[0:3]
	v_mfma_f32_16x16x32_bf16 v[28:31], v[190:193], v[206:209], v[28:31]
	v_mfma_f32_16x16x32_bf16 v[24:27], v[198:201], v[206:209], v[24:27]
	v_mfma_f32_16x16x32_bf16 v[20:23], v[190:193], v[214:217], v[20:23]
	v_mfma_f32_16x16x32_bf16 v[16:19], v[198:201], v[214:217], v[16:19]
	v_mfma_f32_16x16x32_bf16 v[12:15], v[190:193], v[222:225], v[12:15]
	v_mfma_f32_16x16x32_bf16 v[8:11], v[198:201], v[222:225], v[8:11]
	v_mfma_f32_16x16x32_bf16 v[4:7], v[190:193], v[230:233], v[4:7]
	v_mfma_f32_16x16x32_bf16 v[0:3], v[198:201], v[230:233], v[0:3]
	s_barrier
	s_add_i32 s62, 0, 0x18000
	v_add_u32_e32 v144, s62, v163
	s_add_i32 s63, 0, 0x1c000
	ds_read_b128 v[104:107], v144
	ds_read_b128 v[108:111], v144 offset:1024
	ds_read_b128 v[156:159], v144 offset:2048
	ds_read_b128 v[166:169], v144 offset:3072
	v_add_u32_e32 v144, s63, v163
	ds_read_b128 v[186:189], v144
	ds_read_b128 v[190:193], v144 offset:1024
	ds_read_b128 v[194:197], v144 offset:2048
	ds_read_b128 v[198:201], v144 offset:3072
	s_add_u32 s24, s24, 0x200000
	s_addc_u32 s25, s25, 0
	s_mov_b32 m0, s27
	v_lshl_add_u64 v[238:239], s[24:25], 0, v[142:143]
	ds_read_b128 v[202:205], v165 offset:32768
	ds_read_b128 v[206:209], v165 offset:33792
	ds_read_b128 v[210:213], v165 offset:34816
	ds_read_b128 v[214:217], v165 offset:35840
	ds_read_b128 v[218:221], v165 offset:36864
	ds_read_b128 v[222:225], v165 offset:37888
	ds_read_b128 v[226:229], v165 offset:38912
	ds_read_b128 v[230:233], v165 offset:39936
	global_load_lds_dwordx4 v[238:239], off
	v_lshl_add_u64 v[238:239], s[24:25], 0, v[138:139]
	s_mov_b32 m0, s28
	s_nop 0
	global_load_lds_dwordx4 v[238:239], off
	s_waitcnt vmcnt(8)
	s_waitcnt lgkmcnt(0)
	s_barrier
	s_waitcnt lgkmcnt(0)
	v_mfma_f32_16x16x32_bf16 v[132:135], v[104:107], v[202:205], v[132:135]
	v_mfma_f32_16x16x32_bf16 v[128:131], v[156:159], v[202:205], v[128:131]
	v_mfma_f32_16x16x32_bf16 v[124:127], v[104:107], v[210:213], v[124:127]
	v_mfma_f32_16x16x32_bf16 v[120:123], v[156:159], v[210:213], v[120:123]
	v_mfma_f32_16x16x32_bf16 v[116:119], v[104:107], v[218:221], v[116:119]
	v_mfma_f32_16x16x32_bf16 v[112:115], v[156:159], v[218:221], v[112:115]
	v_mfma_f32_16x16x32_bf16 v[100:103], v[104:107], v[226:229], v[100:103]
	v_mfma_f32_16x16x32_bf16 v[96:99], v[156:159], v[226:229], v[96:99]
	v_mfma_f32_16x16x32_bf16 v[132:135], v[108:111], v[206:209], v[132:135]
	v_mfma_f32_16x16x32_bf16 v[128:131], v[166:169], v[206:209], v[128:131]
	v_mfma_f32_16x16x32_bf16 v[124:127], v[108:111], v[214:217], v[124:127]
	v_mfma_f32_16x16x32_bf16 v[120:123], v[166:169], v[214:217], v[120:123]
	v_mfma_f32_16x16x32_bf16 v[116:119], v[108:111], v[222:225], v[116:119]
	v_mfma_f32_16x16x32_bf16 v[112:115], v[166:169], v[222:225], v[112:115]
	v_mfma_f32_16x16x32_bf16 v[100:103], v[108:111], v[230:233], v[100:103]
	v_mfma_f32_16x16x32_bf16 v[96:99], v[166:169], v[230:233], v[96:99]
	v_mfma_f32_16x16x32_bf16 v[60:63], v[186:189], v[202:205], v[60:63]
	v_mfma_f32_16x16x32_bf16 v[56:59], v[194:197], v[202:205], v[56:59]
	v_mfma_f32_16x16x32_bf16 v[52:55], v[186:189], v[210:213], v[52:55]
	v_mfma_f32_16x16x32_bf16 v[48:51], v[194:197], v[210:213], v[48:51]
	v_mfma_f32_16x16x32_bf16 v[44:47], v[186:189], v[218:221], v[44:47]
	v_mfma_f32_16x16x32_bf16 v[40:43], v[194:197], v[218:221], v[40:43]
	v_mfma_f32_16x16x32_bf16 v[36:39], v[186:189], v[226:229], v[36:39]
	v_mfma_f32_16x16x32_bf16 v[32:35], v[194:197], v[226:229], v[32:35]
	v_mfma_f32_16x16x32_bf16 v[60:63], v[190:193], v[206:209], v[60:63]
	v_mfma_f32_16x16x32_bf16 v[56:59], v[198:201], v[206:209], v[56:59]
	v_mfma_f32_16x16x32_bf16 v[52:55], v[190:193], v[214:217], v[52:55]
	v_mfma_f32_16x16x32_bf16 v[48:51], v[198:201], v[214:217], v[48:51]
	v_mfma_f32_16x16x32_bf16 v[44:47], v[190:193], v[222:225], v[44:47]
	v_mfma_f32_16x16x32_bf16 v[40:43], v[198:201], v[222:225], v[40:43]
	v_mfma_f32_16x16x32_bf16 v[36:39], v[190:193], v[230:233], v[36:39]
	v_mfma_f32_16x16x32_bf16 v[32:35], v[198:201], v[230:233], v[32:35]
	s_barrier
	s_add_i32 s24, s62, s4
	v_lshl_add_u64 v[160:161], v[160:161], 0, s[68:69]
	s_mov_b32 m0, s24
	ds_read_b128 v[202:205], v165 offset:49152
	ds_read_b128 v[206:209], v165 offset:50176
	ds_read_b128 v[210:213], v165 offset:51200
	ds_read_b128 v[214:217], v165 offset:52224
	ds_read_b128 v[218:221], v165 offset:53248
	ds_read_b128 v[222:225], v165 offset:54272
	ds_read_b128 v[226:229], v165 offset:55296
	ds_read_b128 v[230:233], v165 offset:56320
	global_load_lds_dwordx4 v[160:161], off
	s_add_i32 m0, s24, 0x2000
	s_add_u32 s22, s22, 0x200080
	v_lshl_add_u64 v[160:161], v[170:171], 0, s[68:69]
	s_addc_u32 s23, s23, 0
	s_add_i32 s24, s63, s4
	global_load_lds_dwordx4 v[160:161], off
	v_lshl_add_u64 v[160:161], s[22:23], 0, v[140:141]
	s_mov_b32 m0, s24
	s_nop 0
	global_load_lds_dwordx4 v[160:161], off
	v_lshl_add_u64 v[160:161], s[22:23], 0, v[136:137]
	s_add_i32 m0, s24, 0x2000
	s_nop 0
	global_load_lds_dwordx4 v[160:161], off
	v_lshl_add_u64 v[160:161], v[234:235], 0, s[68:69]
	s_mov_b32 m0, s50
	s_nop 0
	global_load_lds_dwordx4 v[160:161], off
	v_lshl_add_u64 v[160:161], v[236:237], 0, s[68:69]
	s_mov_b32 m0, s51
	s_nop 0
	global_load_lds_dwordx4 v[160:161], off
	s_waitcnt vmcnt(8)
	s_waitcnt lgkmcnt(0)
	s_barrier
	s_waitcnt lgkmcnt(0)
	v_mfma_f32_16x16x32_bf16 v[92:95], v[104:107], v[202:205], v[92:95]
	v_mfma_f32_16x16x32_bf16 v[88:91], v[156:159], v[202:205], v[88:91]
	v_mfma_f32_16x16x32_bf16 v[84:87], v[104:107], v[210:213], v[84:87]
	v_mfma_f32_16x16x32_bf16 v[80:83], v[156:159], v[210:213], v[80:83]
	v_mfma_f32_16x16x32_bf16 v[76:79], v[104:107], v[218:221], v[76:79]
	v_mfma_f32_16x16x32_bf16 v[72:75], v[156:159], v[218:221], v[72:75]
	v_mfma_f32_16x16x32_bf16 v[68:71], v[104:107], v[226:229], v[68:71]
	v_mfma_f32_16x16x32_bf16 v[64:67], v[156:159], v[226:229], v[64:67]
	v_mfma_f32_16x16x32_bf16 v[92:95], v[108:111], v[206:209], v[92:95]
	v_mfma_f32_16x16x32_bf16 v[88:91], v[166:169], v[206:209], v[88:91]
	v_mfma_f32_16x16x32_bf16 v[84:87], v[108:111], v[214:217], v[84:87]
	v_mfma_f32_16x16x32_bf16 v[80:83], v[166:169], v[214:217], v[80:83]
	v_mfma_f32_16x16x32_bf16 v[76:79], v[108:111], v[222:225], v[76:79]
	v_mfma_f32_16x16x32_bf16 v[72:75], v[166:169], v[222:225], v[72:75]
	v_mfma_f32_16x16x32_bf16 v[68:71], v[108:111], v[230:233], v[68:71]
	v_mfma_f32_16x16x32_bf16 v[64:67], v[166:169], v[230:233], v[64:67]
	v_mfma_f32_16x16x32_bf16 v[28:31], v[186:189], v[202:205], v[28:31]
	v_mfma_f32_16x16x32_bf16 v[24:27], v[194:197], v[202:205], v[24:27]
	v_mfma_f32_16x16x32_bf16 v[20:23], v[186:189], v[210:213], v[20:23]
	v_mfma_f32_16x16x32_bf16 v[16:19], v[194:197], v[210:213], v[16:19]
	v_mfma_f32_16x16x32_bf16 v[12:15], v[186:189], v[218:221], v[12:15]
	v_mfma_f32_16x16x32_bf16 v[8:11], v[194:197], v[218:221], v[8:11]
	v_mfma_f32_16x16x32_bf16 v[4:7], v[186:189], v[226:229], v[4:7]
	v_mfma_f32_16x16x32_bf16 v[0:3], v[194:197], v[226:229], v[0:3]
	v_mfma_f32_16x16x32_bf16 v[28:31], v[190:193], v[206:209], v[28:31]
	v_mfma_f32_16x16x32_bf16 v[24:27], v[198:201], v[206:209], v[24:27]
	v_mfma_f32_16x16x32_bf16 v[20:23], v[190:193], v[214:217], v[20:23]
	v_mfma_f32_16x16x32_bf16 v[16:19], v[198:201], v[214:217], v[16:19]
	v_mfma_f32_16x16x32_bf16 v[12:15], v[190:193], v[222:225], v[12:15]
	v_mfma_f32_16x16x32_bf16 v[8:11], v[198:201], v[222:225], v[8:11]
	v_mfma_f32_16x16x32_bf16 v[4:7], v[190:193], v[230:233], v[4:7]
	v_mfma_f32_16x16x32_bf16 v[0:3], v[198:201], v[230:233], v[0:3]
	s_barrier
	s_add_i32 s22, s61, 2
	s_add_u32 s20, s20, 0x100
	s_addc_u32 s21, s21, 0
	s_add_u32 s58, s58, 0x100
	s_addc_u32 s60, s60, 0
	s_cmp_ge_u32 s61, s39
	s_mov_b32 s61, s22
	s_cbranch_scc0 .LBB0_1057
	s_and_b64 vcc, exec, s[14:15]
	s_cbranch_vccz .LBB0_1060
	s_barrier

.LBB0_1067:
	s_setprio 0
	s_mov_b64 s[4:5], s[76:77]
	s_getreg_b32 s0, hwreg(HW_REG_XCC_ID, 0, 4)
	s_waitcnt vmcnt(0)
	s_waitcnt vmcnt(0)
	s_barrier
	s_mov_b64 s[2:3], exec
	v_readlane_b32 s6, v241, 2
	v_readlane_b32 s7, v241, 3
	s_and_b64 s[6:7], s[2:3], s[6:7]
	s_mov_b64 exec, s[6:7]
	s_cbranch_execz .LBB0_1119
	s_add_i32 s1, 0, 0x20000
	v_mov_b32_e32 v0, s1
	s_load_dwordx2 s[4:5], s[4:5], 0xa8
	s_waitcnt vmcnt(0) expcnt(0) lgkmcnt(0)
	ds_read_b32 v2, v0
	s_add_i32 s1, 0, 0x20004
	v_mov_b32_e32 v0, s1
	ds_read_b32 v0, v0
	s_and_b32 s0, s0, 15
	s_waitcnt lgkmcnt(1)
	v_cmp_ne_u32_e32 vcc, 0, v2
	s_cbranch_vccnz .LBB0_1083
	s_add_u32 s6, s4, 0x1000
	s_addc_u32 s7, s5, 0
	s_add_u32 s8, s4, 0x1100
	s_addc_u32 s9, s5, 0
	s_add_u32 s10, s4, 0x1200
	s_addc_u32 s11, s5, 0
	s_add_u32 s12, s4, 0x1300
	s_addc_u32 s13, s5, 0
	s_mov_b32 s1, 1
	v_mov_b32_e32 v16, 0
	s_branch .LBB0_1071
